# v45: v26 with the K-loop back edges rotated (pointer/counter SALU ops moved into the last MFMA segment, only the branch after the final barrier) in the six GEMM loops
# baseline (speedup 1.0000x reference)
.LBB0_123:
	ds_read_b128 v[146:149], v153
	ds_read_b128 v[156:159], v153 offset:1024
	ds_read_b128 v[160:163], v153 offset:2048
	ds_read_b128 v[164:167], v153 offset:3072
	ds_read_b128 v[168:171], v154
	ds_read_b128 v[172:175], v154 offset:1024
	ds_read_b128 v[176:179], v154 offset:2048
	ds_read_b128 v[180:183], v154 offset:3072
	s_add_u32 s22, s20, 0xfffc0080
	s_addc_u32 s23, s21, -1
	s_cmp_eq_u32 s64, 12
	s_cselect_b32 s31, s13, s23
	s_cselect_b32 s30, s48, s22
	s_cselect_b32 s23, s11, s51
	s_cselect_b32 s22, s49, s50
	v_lshl_add_u64 v[216:217], s[20:21], 0, v[138:139]
	s_add_i32 m0, s37, 0xc000
	ds_read_b128 v[184:187], v155
	ds_read_b128 v[188:191], v155 offset:1024
	ds_read_b128 v[192:195], v155 offset:2048
	ds_read_b128 v[196:199], v155 offset:3072
	ds_read_b128 v[200:203], v155 offset:4096
	ds_read_b128 v[204:207], v155 offset:5120
	ds_read_b128 v[208:211], v155 offset:6144
	ds_read_b128 v[212:215], v155 offset:7168
	global_load_lds_dwordx4 v[216:217], off
	v_lshl_add_u64 v[216:217], s[20:21], 0, v[140:141]
	s_add_i32 m0, s37, 0xe000
	s_nop 0
	global_load_lds_dwordx4 v[216:217], off
	s_waitcnt vmcnt(8)
	s_waitcnt lgkmcnt(0)
	s_barrier
	s_setprio 1
	s_waitcnt lgkmcnt(0)
	v_mfma_f32_16x16x32_bf16 v[126:129], v[146:149], v[184:187], v[126:129]
	v_mfma_f32_16x16x32_bf16 v[118:121], v[160:163], v[184:187], v[118:121]
	v_mfma_f32_16x16x32_bf16 v[110:113], v[146:149], v[192:195], v[110:113]
	v_mfma_f32_16x16x32_bf16 v[102:105], v[160:163], v[192:195], v[102:105]
	v_mfma_f32_16x16x32_bf16 v[94:97], v[146:149], v[200:203], v[94:97]
	v_mfma_f32_16x16x32_bf16 v[86:89], v[160:163], v[200:203], v[86:89]
	v_mfma_f32_16x16x32_bf16 v[78:81], v[146:149], v[208:211], v[78:81]
	v_mfma_f32_16x16x32_bf16 v[70:73], v[160:163], v[208:211], v[70:73]
	v_mfma_f32_16x16x32_bf16 v[126:129], v[156:159], v[188:191], v[126:129]
	v_mfma_f32_16x16x32_bf16 v[118:121], v[164:167], v[188:191], v[118:121]
	v_mfma_f32_16x16x32_bf16 v[110:113], v[156:159], v[196:199], v[110:113]
	v_mfma_f32_16x16x32_bf16 v[102:105], v[164:167], v[196:199], v[102:105]
	v_mfma_f32_16x16x32_bf16 v[94:97], v[156:159], v[204:207], v[94:97]
	v_mfma_f32_16x16x32_bf16 v[86:89], v[164:167], v[204:207], v[86:89]
	v_mfma_f32_16x16x32_bf16 v[78:81], v[156:159], v[212:215], v[78:81]
	v_mfma_f32_16x16x32_bf16 v[70:73], v[164:167], v[212:215], v[70:73]
	s_setprio 0
	s_setprio 1
	v_mfma_f32_16x16x32_bf16 v[122:125], v[168:171], v[184:187], v[122:125]
	v_mfma_f32_16x16x32_bf16 v[114:117], v[176:179], v[184:187], v[114:117]
	v_mfma_f32_16x16x32_bf16 v[106:109], v[168:171], v[192:195], v[106:109]
	v_mfma_f32_16x16x32_bf16 v[98:101], v[176:179], v[192:195], v[98:101]
	v_mfma_f32_16x16x32_bf16 v[90:93], v[168:171], v[200:203], v[90:93]
	v_mfma_f32_16x16x32_bf16 v[82:85], v[176:179], v[200:203], v[82:85]
	v_mfma_f32_16x16x32_bf16 v[74:77], v[168:171], v[208:211], v[74:77]
	v_mfma_f32_16x16x32_bf16 v[66:69], v[176:179], v[208:211], v[66:69]
	v_mfma_f32_16x16x32_bf16 v[122:125], v[172:175], v[188:191], v[122:125]
	v_mfma_f32_16x16x32_bf16 v[114:117], v[180:183], v[188:191], v[114:117]
	v_mfma_f32_16x16x32_bf16 v[106:109], v[172:175], v[196:199], v[106:109]
	v_mfma_f32_16x16x32_bf16 v[98:101], v[180:183], v[196:199], v[98:101]
	v_mfma_f32_16x16x32_bf16 v[90:93], v[172:175], v[204:207], v[90:93]
	v_mfma_f32_16x16x32_bf16 v[82:85], v[180:183], v[204:207], v[82:85]
	v_mfma_f32_16x16x32_bf16 v[74:77], v[172:175], v[212:215], v[74:77]
	v_mfma_f32_16x16x32_bf16 v[66:69], v[180:183], v[212:215], v[66:69]
	s_setprio 0
	s_barrier
	s_add_i32 s65, s45, s36
	v_lshl_add_u64 v[216:217], s[22:23], 0, v[132:133]
	s_mov_b32 m0, s65
	ds_read_b128 v[184:187], v155 offset:16384
	ds_read_b128 v[188:191], v155 offset:17408
	ds_read_b128 v[192:195], v155 offset:18432
	ds_read_b128 v[196:199], v155 offset:19456
	ds_read_b128 v[200:203], v155 offset:20480
	ds_read_b128 v[204:207], v155 offset:21504
	ds_read_b128 v[208:211], v155 offset:22528
	ds_read_b128 v[212:215], v155 offset:23552
	global_load_lds_dwordx4 v[216:217], off
	s_add_i32 m0, s65, 0x2000
	s_add_u32 s68, s22, 0x40000
	v_lshl_add_u64 v[218:219], s[22:23], 0, v[136:137]
	s_addc_u32 s69, s23, 0
	s_add_i32 s65, s46, s36
	global_load_lds_dwordx4 v[218:219], off
	v_lshl_add_u64 v[220:221], s[68:69], 0, v[132:133]
	s_mov_b32 m0, s65
	v_lshl_add_u64 v[222:223], s[30:31], 0, v[134:135]
	global_load_lds_dwordx4 v[220:221], off
	v_lshl_add_u64 v[220:221], s[68:69], 0, v[136:137]
	s_add_i32 m0, s65, 0x2000
	s_nop 0
	global_load_lds_dwordx4 v[220:221], off
	v_lshl_add_u64 v[220:221], s[30:31], 0, v[130:131]
	s_mov_b32 m0, s37
	s_nop 0
	global_load_lds_dwordx4 v[220:221], off
	s_mov_b32 m0, s38
	s_nop 0
	global_load_lds_dwordx4 v[222:223], off
	s_waitcnt vmcnt(8)
	s_waitcnt lgkmcnt(0)
	s_barrier
	s_setprio 1
	s_waitcnt lgkmcnt(0)
	v_mfma_f32_16x16x32_bf16 v[62:65], v[146:149], v[184:187], v[62:65]
	v_mfma_f32_16x16x32_bf16 v[54:57], v[160:163], v[184:187], v[54:57]
	v_mfma_f32_16x16x32_bf16 v[46:49], v[146:149], v[192:195], v[46:49]
	v_mfma_f32_16x16x32_bf16 v[38:41], v[160:163], v[192:195], v[38:41]
	v_mfma_f32_16x16x32_bf16 v[30:33], v[146:149], v[200:203], v[30:33]
	v_mfma_f32_16x16x32_bf16 v[22:25], v[160:163], v[200:203], v[22:25]
	v_mfma_f32_16x16x32_bf16 v[14:17], v[146:149], v[208:211], v[14:17]
	v_mfma_f32_16x16x32_bf16 v[6:9], v[160:163], v[208:211], v[6:9]
	v_mfma_f32_16x16x32_bf16 v[62:65], v[156:159], v[188:191], v[62:65]
	v_mfma_f32_16x16x32_bf16 v[54:57], v[164:167], v[188:191], v[54:57]
	v_mfma_f32_16x16x32_bf16 v[46:49], v[156:159], v[196:199], v[46:49]
	v_mfma_f32_16x16x32_bf16 v[38:41], v[164:167], v[196:199], v[38:41]
	v_mfma_f32_16x16x32_bf16 v[30:33], v[156:159], v[204:207], v[30:33]
	v_mfma_f32_16x16x32_bf16 v[22:25], v[164:167], v[204:207], v[22:25]
	v_mfma_f32_16x16x32_bf16 v[14:17], v[156:159], v[212:215], v[14:17]
	v_mfma_f32_16x16x32_bf16 v[6:9], v[164:167], v[212:215], v[6:9]
	s_setprio 0
	s_setprio 1
	v_mfma_f32_16x16x32_bf16 v[58:61], v[168:171], v[184:187], v[58:61]
	v_mfma_f32_16x16x32_bf16 v[50:53], v[176:179], v[184:187], v[50:53]
	v_mfma_f32_16x16x32_bf16 v[42:45], v[168:171], v[192:195], v[42:45]
	v_mfma_f32_16x16x32_bf16 v[34:37], v[176:179], v[192:195], v[34:37]
	v_mfma_f32_16x16x32_bf16 v[26:29], v[168:171], v[200:203], v[26:29]
	v_mfma_f32_16x16x32_bf16 v[18:21], v[176:179], v[200:203], v[18:21]
	v_mfma_f32_16x16x32_bf16 v[10:13], v[168:171], v[208:211], v[10:13]
	v_mfma_f32_16x16x32_bf16 v[2:5], v[176:179], v[208:211], v[2:5]
	v_mfma_f32_16x16x32_bf16 v[58:61], v[172:175], v[188:191], v[58:61]
	v_mfma_f32_16x16x32_bf16 v[50:53], v[180:183], v[188:191], v[50:53]
	v_mfma_f32_16x16x32_bf16 v[42:45], v[172:175], v[196:199], v[42:45]
	v_mfma_f32_16x16x32_bf16 v[34:37], v[180:183], v[196:199], v[34:37]
	v_mfma_f32_16x16x32_bf16 v[26:29], v[172:175], v[204:207], v[26:29]
	v_mfma_f32_16x16x32_bf16 v[18:21], v[180:183], v[204:207], v[18:21]
	v_mfma_f32_16x16x32_bf16 v[10:13], v[172:175], v[212:215], v[10:13]
	v_mfma_f32_16x16x32_bf16 v[2:5], v[180:183], v[212:215], v[2:5]
	s_setprio 0
	s_barrier
	s_add_i32 s65, 0, 0x18000
	s_add_i32 s68, 0, 0x1c000
	v_add_u32_e32 v164, s65, v151
	v_add_u32_e32 v180, s68, v151
	ds_read_b128 v[146:149], v164
	ds_read_b128 v[156:159], v164 offset:1024
	ds_read_b128 v[160:163], v164 offset:2048
	ds_read_b128 v[164:167], v164 offset:3072
	ds_read_b128 v[168:171], v180
	ds_read_b128 v[172:175], v180 offset:1024
	ds_read_b128 v[176:179], v180 offset:2048
	ds_read_b128 v[180:183], v180 offset:3072
	s_add_u32 s30, s30, 0x40000
	s_addc_u32 s31, s31, 0
	s_mov_b32 m0, s39
	v_lshl_add_u64 v[224:225], s[30:31], 0, v[130:131]
	ds_read_b128 v[184:187], v155 offset:32768
	ds_read_b128 v[188:191], v155 offset:33792
	ds_read_b128 v[192:195], v155 offset:34816
	ds_read_b128 v[196:199], v155 offset:35840
	ds_read_b128 v[200:203], v155 offset:36864
	ds_read_b128 v[204:207], v155 offset:37888
	ds_read_b128 v[208:211], v155 offset:38912
	ds_read_b128 v[212:215], v155 offset:39936
	global_load_lds_dwordx4 v[224:225], off
	v_lshl_add_u64 v[224:225], s[30:31], 0, v[134:135]
	s_mov_b32 m0, s40
	s_nop 0
	global_load_lds_dwordx4 v[224:225], off
	s_waitcnt vmcnt(8)
	s_waitcnt lgkmcnt(0)
	s_barrier
	s_setprio 1
	s_waitcnt lgkmcnt(0)
	v_mfma_f32_16x16x32_bf16 v[126:129], v[146:149], v[184:187], v[126:129]
	v_mfma_f32_16x16x32_bf16 v[118:121], v[160:163], v[184:187], v[118:121]
	v_mfma_f32_16x16x32_bf16 v[110:113], v[146:149], v[192:195], v[110:113]
	v_mfma_f32_16x16x32_bf16 v[102:105], v[160:163], v[192:195], v[102:105]
	v_mfma_f32_16x16x32_bf16 v[94:97], v[146:149], v[200:203], v[94:97]
	v_mfma_f32_16x16x32_bf16 v[86:89], v[160:163], v[200:203], v[86:89]
	v_mfma_f32_16x16x32_bf16 v[78:81], v[146:149], v[208:211], v[78:81]
	v_mfma_f32_16x16x32_bf16 v[70:73], v[160:163], v[208:211], v[70:73]
	v_mfma_f32_16x16x32_bf16 v[126:129], v[156:159], v[188:191], v[126:129]
	v_mfma_f32_16x16x32_bf16 v[118:121], v[164:167], v[188:191], v[118:121]
	v_mfma_f32_16x16x32_bf16 v[110:113], v[156:159], v[196:199], v[110:113]
	v_mfma_f32_16x16x32_bf16 v[102:105], v[164:167], v[196:199], v[102:105]
	v_mfma_f32_16x16x32_bf16 v[94:97], v[156:159], v[204:207], v[94:97]
	v_mfma_f32_16x16x32_bf16 v[86:89], v[164:167], v[204:207], v[86:89]
	v_mfma_f32_16x16x32_bf16 v[78:81], v[156:159], v[212:215], v[78:81]
	v_mfma_f32_16x16x32_bf16 v[70:73], v[164:167], v[212:215], v[70:73]
	s_setprio 0
	s_setprio 1
	v_mfma_f32_16x16x32_bf16 v[122:125], v[168:171], v[184:187], v[122:125]
	v_mfma_f32_16x16x32_bf16 v[114:117], v[176:179], v[184:187], v[114:117]
	v_mfma_f32_16x16x32_bf16 v[106:109], v[168:171], v[192:195], v[106:109]
	v_mfma_f32_16x16x32_bf16 v[98:101], v[176:179], v[192:195], v[98:101]
	v_mfma_f32_16x16x32_bf16 v[90:93], v[168:171], v[200:203], v[90:93]
	v_mfma_f32_16x16x32_bf16 v[82:85], v[176:179], v[200:203], v[82:85]
	v_mfma_f32_16x16x32_bf16 v[74:77], v[168:171], v[208:211], v[74:77]
	v_mfma_f32_16x16x32_bf16 v[66:69], v[176:179], v[208:211], v[66:69]
	v_mfma_f32_16x16x32_bf16 v[122:125], v[172:175], v[188:191], v[122:125]
	v_mfma_f32_16x16x32_bf16 v[114:117], v[180:183], v[188:191], v[114:117]
	v_mfma_f32_16x16x32_bf16 v[106:109], v[172:175], v[196:199], v[106:109]
	v_mfma_f32_16x16x32_bf16 v[98:101], v[180:183], v[196:199], v[98:101]
	v_mfma_f32_16x16x32_bf16 v[90:93], v[172:175], v[204:207], v[90:93]
	v_mfma_f32_16x16x32_bf16 v[82:85], v[180:183], v[204:207], v[82:85]
	v_mfma_f32_16x16x32_bf16 v[74:77], v[172:175], v[212:215], v[74:77]
	v_mfma_f32_16x16x32_bf16 v[66:69], v[180:183], v[212:215], v[66:69]
	s_setprio 0
	s_barrier
	s_add_i32 s30, s65, s36
	v_lshl_add_u64 v[216:217], v[216:217], 0, s[6:7]
	s_mov_b32 m0, s30
	ds_read_b128 v[184:187], v155 offset:49152
	ds_read_b128 v[188:191], v155 offset:50176
	ds_read_b128 v[192:195], v155 offset:51200
	ds_read_b128 v[196:199], v155 offset:52224
	ds_read_b128 v[200:203], v155 offset:53248
	ds_read_b128 v[204:207], v155 offset:54272
	ds_read_b128 v[208:211], v155 offset:55296
	ds_read_b128 v[212:215], v155 offset:56320
	global_load_lds_dwordx4 v[216:217], off
	s_add_i32 m0, s30, 0x2000
	s_add_u32 s22, s22, 0x40080
	v_lshl_add_u64 v[216:217], v[218:219], 0, s[6:7]
	s_addc_u32 s23, s23, 0
	s_add_i32 s30, s68, s36
	global_load_lds_dwordx4 v[216:217], off
	v_lshl_add_u64 v[216:217], s[22:23], 0, v[132:133]
	s_mov_b32 m0, s30
	s_nop 0
	global_load_lds_dwordx4 v[216:217], off
	v_lshl_add_u64 v[216:217], s[22:23], 0, v[136:137]
	s_add_i32 m0, s30, 0x2000
	s_nop 0
	global_load_lds_dwordx4 v[216:217], off
	v_lshl_add_u64 v[216:217], v[220:221], 0, s[6:7]
	s_mov_b32 m0, s42
	s_nop 0
	global_load_lds_dwordx4 v[216:217], off
	v_lshl_add_u64 v[216:217], v[222:223], 0, s[6:7]
	s_mov_b32 m0, s43
	s_nop 0
	global_load_lds_dwordx4 v[216:217], off
	s_waitcnt vmcnt(8)
	s_waitcnt lgkmcnt(0)
	s_barrier
	s_setprio 1
	s_waitcnt lgkmcnt(0)
	v_mfma_f32_16x16x32_bf16 v[62:65], v[146:149], v[184:187], v[62:65]
	v_mfma_f32_16x16x32_bf16 v[54:57], v[160:163], v[184:187], v[54:57]
	v_mfma_f32_16x16x32_bf16 v[46:49], v[146:149], v[192:195], v[46:49]
	v_mfma_f32_16x16x32_bf16 v[38:41], v[160:163], v[192:195], v[38:41]
	v_mfma_f32_16x16x32_bf16 v[30:33], v[146:149], v[200:203], v[30:33]
	v_mfma_f32_16x16x32_bf16 v[22:25], v[160:163], v[200:203], v[22:25]
	v_mfma_f32_16x16x32_bf16 v[14:17], v[146:149], v[208:211], v[14:17]
	v_mfma_f32_16x16x32_bf16 v[6:9], v[160:163], v[208:211], v[6:9]
	v_mfma_f32_16x16x32_bf16 v[62:65], v[156:159], v[188:191], v[62:65]
	v_mfma_f32_16x16x32_bf16 v[54:57], v[164:167], v[188:191], v[54:57]
	v_mfma_f32_16x16x32_bf16 v[46:49], v[156:159], v[196:199], v[46:49]
	v_mfma_f32_16x16x32_bf16 v[38:41], v[164:167], v[196:199], v[38:41]
	v_mfma_f32_16x16x32_bf16 v[30:33], v[156:159], v[204:207], v[30:33]
	v_mfma_f32_16x16x32_bf16 v[22:25], v[164:167], v[204:207], v[22:25]
	v_mfma_f32_16x16x32_bf16 v[14:17], v[156:159], v[212:215], v[14:17]
	v_mfma_f32_16x16x32_bf16 v[6:9], v[164:167], v[212:215], v[6:9]
	s_setprio 0
	s_setprio 1
	v_mfma_f32_16x16x32_bf16 v[58:61], v[168:171], v[184:187], v[58:61]
	v_mfma_f32_16x16x32_bf16 v[50:53], v[176:179], v[184:187], v[50:53]
	v_mfma_f32_16x16x32_bf16 v[42:45], v[168:171], v[192:195], v[42:45]
	v_mfma_f32_16x16x32_bf16 v[34:37], v[176:179], v[192:195], v[34:37]
	v_mfma_f32_16x16x32_bf16 v[26:29], v[168:171], v[200:203], v[26:29]
	v_mfma_f32_16x16x32_bf16 v[18:21], v[176:179], v[200:203], v[18:21]
	v_mfma_f32_16x16x32_bf16 v[10:13], v[168:171], v[208:211], v[10:13]
	v_mfma_f32_16x16x32_bf16 v[2:5], v[176:179], v[208:211], v[2:5]
	v_mfma_f32_16x16x32_bf16 v[58:61], v[172:175], v[188:191], v[58:61]
	v_mfma_f32_16x16x32_bf16 v[50:53], v[180:183], v[188:191], v[50:53]
	v_mfma_f32_16x16x32_bf16 v[42:45], v[172:175], v[196:199], v[42:45]
	v_mfma_f32_16x16x32_bf16 v[34:37], v[180:183], v[196:199], v[34:37]
	v_mfma_f32_16x16x32_bf16 v[26:29], v[172:175], v[204:207], v[26:29]
	v_mfma_f32_16x16x32_bf16 v[18:21], v[180:183], v[204:207], v[18:21]
	v_mfma_f32_16x16x32_bf16 v[10:13], v[172:175], v[212:215], v[10:13]
	v_mfma_f32_16x16x32_bf16 v[2:5], v[180:183], v[212:215], v[2:5]
	s_add_i32 s64, s64, 2
	s_add_u32 s20, s20, 0x100
	s_addc_u32 s21, s21, 0
	s_add_u32 s50, s50, 0x100
	s_addc_u32 s51, s51, 0
	s_cmp_gt_u32 s64, 13
	s_setprio 0
	s_barrier
	s_cbranch_scc0 .LBB0_123
	s_and_b64 vcc, exec, s[8:9]
	s_cbranch_vccz .LBB0_126
	s_barrier

.LBB0_221:
	ds_read_b128 v[144:147], v150
	ds_read_b128 v[154:157], v150 offset:1024
	ds_read_b128 v[158:161], v150 offset:2048
	ds_read_b128 v[162:165], v150 offset:3072
	ds_read_b128 v[166:169], v151
	ds_read_b128 v[170:173], v151 offset:1024
	ds_read_b128 v[174:177], v151 offset:2048
	ds_read_b128 v[178:181], v151 offset:3072
	s_add_u32 s18, s16, 0xfff50080
	s_addc_u32 s19, s17, -1
	s_cmp_eq_u32 s51, s65
	s_cselect_b32 s21, s13, s19
	s_cselect_b32 s20, s12, s18
	s_cselect_b32 s19, s15, s64
	s_cselect_b32 s18, s14, s11
	v_lshl_add_u64 v[214:215], s[16:17], 0, v[138:139]
	s_add_i32 m0, s30, 0xc000
	ds_read_b128 v[182:185], v152
	ds_read_b128 v[186:189], v152 offset:1024
	ds_read_b128 v[190:193], v152 offset:2048
	ds_read_b128 v[194:197], v152 offset:3072
	ds_read_b128 v[198:201], v152 offset:4096
	ds_read_b128 v[202:205], v152 offset:5120
	ds_read_b128 v[206:209], v152 offset:6144
	ds_read_b128 v[210:213], v152 offset:7168
	global_load_lds_dwordx4 v[214:215], off
	v_lshl_add_u64 v[214:215], s[16:17], 0, v[140:141]
	s_add_i32 m0, s30, 0xe000
	s_nop 0
	global_load_lds_dwordx4 v[214:215], off
	s_waitcnt vmcnt(8)
	s_waitcnt lgkmcnt(0)
	s_barrier
	s_setprio 1
	s_waitcnt lgkmcnt(0)
	v_mfma_f32_16x16x32_bf16 v[126:129], v[144:147], v[182:185], v[126:129]
	v_mfma_f32_16x16x32_bf16 v[122:125], v[158:161], v[182:185], v[122:125]
	v_mfma_f32_16x16x32_bf16 v[118:121], v[144:147], v[190:193], v[118:121]
	v_mfma_f32_16x16x32_bf16 v[110:113], v[158:161], v[190:193], v[110:113]
	v_mfma_f32_16x16x32_bf16 v[102:105], v[144:147], v[198:201], v[102:105]
	v_mfma_f32_16x16x32_bf16 v[94:97], v[158:161], v[198:201], v[94:97]
	v_mfma_f32_16x16x32_bf16 v[86:89], v[144:147], v[206:209], v[86:89]
	v_mfma_f32_16x16x32_bf16 v[78:81], v[158:161], v[206:209], v[78:81]
	v_mfma_f32_16x16x32_bf16 v[126:129], v[154:157], v[186:189], v[126:129]
	v_mfma_f32_16x16x32_bf16 v[122:125], v[162:165], v[186:189], v[122:125]
	v_mfma_f32_16x16x32_bf16 v[118:121], v[154:157], v[194:197], v[118:121]
	v_mfma_f32_16x16x32_bf16 v[110:113], v[162:165], v[194:197], v[110:113]
	v_mfma_f32_16x16x32_bf16 v[102:105], v[154:157], v[202:205], v[102:105]
	v_mfma_f32_16x16x32_bf16 v[94:97], v[162:165], v[202:205], v[94:97]
	v_mfma_f32_16x16x32_bf16 v[86:89], v[154:157], v[210:213], v[86:89]
	v_mfma_f32_16x16x32_bf16 v[78:81], v[162:165], v[210:213], v[78:81]
	s_setprio 0
	s_setprio 1
	v_mfma_f32_16x16x32_bf16 v[114:117], v[166:169], v[182:185], v[114:117]
	v_mfma_f32_16x16x32_bf16 v[106:109], v[174:177], v[182:185], v[106:109]
	v_mfma_f32_16x16x32_bf16 v[98:101], v[166:169], v[190:193], v[98:101]
	v_mfma_f32_16x16x32_bf16 v[90:93], v[174:177], v[190:193], v[90:93]
	v_mfma_f32_16x16x32_bf16 v[82:85], v[166:169], v[198:201], v[82:85]
	v_mfma_f32_16x16x32_bf16 v[74:77], v[174:177], v[198:201], v[74:77]
	v_mfma_f32_16x16x32_bf16 v[70:73], v[166:169], v[206:209], v[70:73]
	v_mfma_f32_16x16x32_bf16 v[66:69], v[174:177], v[206:209], v[66:69]
	v_mfma_f32_16x16x32_bf16 v[114:117], v[170:173], v[186:189], v[114:117]
	v_mfma_f32_16x16x32_bf16 v[106:109], v[178:181], v[186:189], v[106:109]
	v_mfma_f32_16x16x32_bf16 v[98:101], v[170:173], v[194:197], v[98:101]
	v_mfma_f32_16x16x32_bf16 v[90:93], v[178:181], v[194:197], v[90:93]
	v_mfma_f32_16x16x32_bf16 v[82:85], v[170:173], v[202:205], v[82:85]
	v_mfma_f32_16x16x32_bf16 v[74:77], v[178:181], v[202:205], v[74:77]
	v_mfma_f32_16x16x32_bf16 v[70:73], v[170:173], v[210:213], v[70:73]
	v_mfma_f32_16x16x32_bf16 v[66:69], v[178:181], v[210:213], v[66:69]
	s_setprio 0
	s_barrier
	s_add_i32 s68, s43, s29
	v_lshl_add_u64 v[214:215], s[18:19], 0, v[132:133]
	s_mov_b32 m0, s68
	ds_read_b128 v[182:185], v152 offset:16384
	ds_read_b128 v[186:189], v152 offset:17408
	ds_read_b128 v[190:193], v152 offset:18432
	ds_read_b128 v[194:197], v152 offset:19456
	ds_read_b128 v[198:201], v152 offset:20480
	ds_read_b128 v[202:205], v152 offset:21504
	ds_read_b128 v[206:209], v152 offset:22528
	ds_read_b128 v[210:213], v152 offset:23552
	global_load_lds_dwordx4 v[214:215], off
	s_add_i32 m0, s68, 0x2000
	s_add_u32 s68, s18, 0xb0000
	v_lshl_add_u64 v[216:217], s[18:19], 0, v[136:137]
	s_addc_u32 s69, s19, 0
	s_add_i32 s70, s44, s29
	global_load_lds_dwordx4 v[216:217], off
	v_lshl_add_u64 v[218:219], s[68:69], 0, v[132:133]
	s_mov_b32 m0, s70
	v_lshl_add_u64 v[220:221], s[20:21], 0, v[134:135]
	global_load_lds_dwordx4 v[218:219], off
	v_lshl_add_u64 v[218:219], s[68:69], 0, v[136:137]
	s_add_i32 m0, s70, 0x2000
	s_nop 0
	global_load_lds_dwordx4 v[218:219], off
	v_lshl_add_u64 v[218:219], s[20:21], 0, v[130:131]
	s_mov_b32 m0, s30
	s_nop 0
	global_load_lds_dwordx4 v[218:219], off
	s_mov_b32 m0, s31
	s_nop 0
	global_load_lds_dwordx4 v[220:221], off
	s_waitcnt vmcnt(8)
	s_waitcnt lgkmcnt(0)
	s_barrier
	s_setprio 1
	s_waitcnt lgkmcnt(0)
	v_mfma_f32_16x16x32_bf16 v[62:65], v[144:147], v[182:185], v[62:65]
	v_mfma_f32_16x16x32_bf16 v[58:61], v[158:161], v[182:185], v[58:61]
	v_mfma_f32_16x16x32_bf16 v[54:57], v[144:147], v[190:193], v[54:57]
	v_mfma_f32_16x16x32_bf16 v[46:49], v[158:161], v[190:193], v[46:49]
	v_mfma_f32_16x16x32_bf16 v[38:41], v[144:147], v[198:201], v[38:41]
	v_mfma_f32_16x16x32_bf16 v[30:33], v[158:161], v[198:201], v[30:33]
	v_mfma_f32_16x16x32_bf16 v[22:25], v[144:147], v[206:209], v[22:25]
	v_mfma_f32_16x16x32_bf16 v[14:17], v[158:161], v[206:209], v[14:17]
	v_mfma_f32_16x16x32_bf16 v[62:65], v[154:157], v[186:189], v[62:65]
	v_mfma_f32_16x16x32_bf16 v[58:61], v[162:165], v[186:189], v[58:61]
	v_mfma_f32_16x16x32_bf16 v[54:57], v[154:157], v[194:197], v[54:57]
	v_mfma_f32_16x16x32_bf16 v[46:49], v[162:165], v[194:197], v[46:49]
	v_mfma_f32_16x16x32_bf16 v[38:41], v[154:157], v[202:205], v[38:41]
	v_mfma_f32_16x16x32_bf16 v[30:33], v[162:165], v[202:205], v[30:33]
	v_mfma_f32_16x16x32_bf16 v[22:25], v[154:157], v[210:213], v[22:25]
	v_mfma_f32_16x16x32_bf16 v[14:17], v[162:165], v[210:213], v[14:17]
	s_setprio 0
	s_setprio 1
	v_mfma_f32_16x16x32_bf16 v[50:53], v[166:169], v[182:185], v[50:53]
	v_mfma_f32_16x16x32_bf16 v[42:45], v[174:177], v[182:185], v[42:45]
	v_mfma_f32_16x16x32_bf16 v[34:37], v[166:169], v[190:193], v[34:37]
	v_mfma_f32_16x16x32_bf16 v[26:29], v[174:177], v[190:193], v[26:29]
	v_mfma_f32_16x16x32_bf16 v[18:21], v[166:169], v[198:201], v[18:21]
	v_mfma_f32_16x16x32_bf16 v[10:13], v[174:177], v[198:201], v[10:13]
	v_mfma_f32_16x16x32_bf16 v[6:9], v[166:169], v[206:209], v[6:9]
	v_mfma_f32_16x16x32_bf16 v[2:5], v[174:177], v[206:209], v[2:5]
	v_mfma_f32_16x16x32_bf16 v[50:53], v[170:173], v[186:189], v[50:53]
	v_mfma_f32_16x16x32_bf16 v[42:45], v[178:181], v[186:189], v[42:45]
	v_mfma_f32_16x16x32_bf16 v[34:37], v[170:173], v[194:197], v[34:37]
	v_mfma_f32_16x16x32_bf16 v[26:29], v[178:181], v[194:197], v[26:29]
	v_mfma_f32_16x16x32_bf16 v[18:21], v[170:173], v[202:205], v[18:21]
	v_mfma_f32_16x16x32_bf16 v[10:13], v[178:181], v[202:205], v[10:13]
	v_mfma_f32_16x16x32_bf16 v[6:9], v[170:173], v[210:213], v[6:9]
	v_mfma_f32_16x16x32_bf16 v[2:5], v[178:181], v[210:213], v[2:5]
	s_setprio 0
	s_barrier
	s_add_i32 s68, 0, 0x18000
	v_add_u32_e32 v153, s68, v148
	s_add_i32 s69, 0, 0x1c000
	ds_read_b128 v[144:147], v153
	ds_read_b128 v[154:157], v153 offset:1024
	ds_read_b128 v[158:161], v153 offset:2048
	ds_read_b128 v[162:165], v153 offset:3072
	v_add_u32_e32 v153, s69, v148
	ds_read_b128 v[166:169], v153
	ds_read_b128 v[170:173], v153 offset:1024
	ds_read_b128 v[174:177], v153 offset:2048
	ds_read_b128 v[178:181], v153 offset:3072
	s_add_u32 s20, s20, 0xb0000
	s_addc_u32 s21, s21, 0
	s_mov_b32 m0, s34
	v_lshl_add_u64 v[222:223], s[20:21], 0, v[130:131]
	ds_read_b128 v[182:185], v152 offset:32768
	ds_read_b128 v[186:189], v152 offset:33792
	ds_read_b128 v[190:193], v152 offset:34816
	ds_read_b128 v[194:197], v152 offset:35840
	ds_read_b128 v[198:201], v152 offset:36864
	ds_read_b128 v[202:205], v152 offset:37888
	ds_read_b128 v[206:209], v152 offset:38912
	ds_read_b128 v[210:213], v152 offset:39936
	global_load_lds_dwordx4 v[222:223], off
	v_lshl_add_u64 v[222:223], s[20:21], 0, v[134:135]
	s_mov_b32 m0, s35
	s_nop 0
	global_load_lds_dwordx4 v[222:223], off
	s_waitcnt vmcnt(8)
	s_waitcnt lgkmcnt(0)
	s_barrier
	s_setprio 1
	s_waitcnt lgkmcnt(0)
	v_mfma_f32_16x16x32_bf16 v[126:129], v[144:147], v[182:185], v[126:129]
	v_mfma_f32_16x16x32_bf16 v[122:125], v[158:161], v[182:185], v[122:125]
	v_mfma_f32_16x16x32_bf16 v[118:121], v[144:147], v[190:193], v[118:121]
	v_mfma_f32_16x16x32_bf16 v[110:113], v[158:161], v[190:193], v[110:113]
	v_mfma_f32_16x16x32_bf16 v[102:105], v[144:147], v[198:201], v[102:105]
	v_mfma_f32_16x16x32_bf16 v[94:97], v[158:161], v[198:201], v[94:97]
	v_mfma_f32_16x16x32_bf16 v[86:89], v[144:147], v[206:209], v[86:89]
	v_mfma_f32_16x16x32_bf16 v[78:81], v[158:161], v[206:209], v[78:81]
	v_mfma_f32_16x16x32_bf16 v[126:129], v[154:157], v[186:189], v[126:129]
	v_mfma_f32_16x16x32_bf16 v[122:125], v[162:165], v[186:189], v[122:125]
	v_mfma_f32_16x16x32_bf16 v[118:121], v[154:157], v[194:197], v[118:121]
	v_mfma_f32_16x16x32_bf16 v[110:113], v[162:165], v[194:197], v[110:113]
	v_mfma_f32_16x16x32_bf16 v[102:105], v[154:157], v[202:205], v[102:105]
	v_mfma_f32_16x16x32_bf16 v[94:97], v[162:165], v[202:205], v[94:97]
	v_mfma_f32_16x16x32_bf16 v[86:89], v[154:157], v[210:213], v[86:89]
	v_mfma_f32_16x16x32_bf16 v[78:81], v[162:165], v[210:213], v[78:81]
	s_setprio 0
	s_setprio 1
	v_mfma_f32_16x16x32_bf16 v[114:117], v[166:169], v[182:185], v[114:117]
	v_mfma_f32_16x16x32_bf16 v[106:109], v[174:177], v[182:185], v[106:109]
	v_mfma_f32_16x16x32_bf16 v[98:101], v[166:169], v[190:193], v[98:101]
	v_mfma_f32_16x16x32_bf16 v[90:93], v[174:177], v[190:193], v[90:93]
	v_mfma_f32_16x16x32_bf16 v[82:85], v[166:169], v[198:201], v[82:85]
	v_mfma_f32_16x16x32_bf16 v[74:77], v[174:177], v[198:201], v[74:77]
	v_mfma_f32_16x16x32_bf16 v[70:73], v[166:169], v[206:209], v[70:73]
	v_mfma_f32_16x16x32_bf16 v[66:69], v[174:177], v[206:209], v[66:69]
	v_mfma_f32_16x16x32_bf16 v[114:117], v[170:173], v[186:189], v[114:117]
	v_mfma_f32_16x16x32_bf16 v[106:109], v[178:181], v[186:189], v[106:109]
	v_mfma_f32_16x16x32_bf16 v[98:101], v[170:173], v[194:197], v[98:101]
	v_mfma_f32_16x16x32_bf16 v[90:93], v[178:181], v[194:197], v[90:93]
	v_mfma_f32_16x16x32_bf16 v[82:85], v[170:173], v[202:205], v[82:85]
	v_mfma_f32_16x16x32_bf16 v[74:77], v[178:181], v[202:205], v[74:77]
	v_mfma_f32_16x16x32_bf16 v[70:73], v[170:173], v[210:213], v[70:73]
	v_mfma_f32_16x16x32_bf16 v[66:69], v[178:181], v[210:213], v[66:69]
	s_setprio 0
	s_barrier
	s_add_i32 s20, s68, s29
	v_lshl_add_u64 v[214:215], v[214:215], 0, s[6:7]
	s_mov_b32 m0, s20
	ds_read_b128 v[182:185], v152 offset:49152
	ds_read_b128 v[186:189], v152 offset:50176
	ds_read_b128 v[190:193], v152 offset:51200
	ds_read_b128 v[194:197], v152 offset:52224
	ds_read_b128 v[198:201], v152 offset:53248
	ds_read_b128 v[202:205], v152 offset:54272
	ds_read_b128 v[206:209], v152 offset:55296
	ds_read_b128 v[210:213], v152 offset:56320
	global_load_lds_dwordx4 v[214:215], off
	s_add_i32 m0, s20, 0x2000
	s_add_u32 s18, s18, 0xb0080
	v_lshl_add_u64 v[214:215], v[216:217], 0, s[6:7]
	s_addc_u32 s19, s19, 0
	s_add_i32 s20, s69, s29
	global_load_lds_dwordx4 v[214:215], off
	v_lshl_add_u64 v[214:215], s[18:19], 0, v[132:133]
	s_mov_b32 m0, s20
	s_nop 0
	global_load_lds_dwordx4 v[214:215], off
	v_lshl_add_u64 v[214:215], s[18:19], 0, v[136:137]
	s_add_i32 m0, s20, 0x2000
	s_nop 0
	global_load_lds_dwordx4 v[214:215], off
	v_lshl_add_u64 v[214:215], v[218:219], 0, s[6:7]
	s_mov_b32 m0, s39
	s_nop 0
	global_load_lds_dwordx4 v[214:215], off
	v_lshl_add_u64 v[214:215], v[220:221], 0, s[6:7]
	s_mov_b32 m0, s40
	s_nop 0
	global_load_lds_dwordx4 v[214:215], off
	s_waitcnt vmcnt(8)
	s_waitcnt lgkmcnt(0)
	s_barrier
	s_setprio 1
	s_waitcnt lgkmcnt(0)
	v_mfma_f32_16x16x32_bf16 v[62:65], v[144:147], v[182:185], v[62:65]
	v_mfma_f32_16x16x32_bf16 v[58:61], v[158:161], v[182:185], v[58:61]
	v_mfma_f32_16x16x32_bf16 v[54:57], v[144:147], v[190:193], v[54:57]
	v_mfma_f32_16x16x32_bf16 v[46:49], v[158:161], v[190:193], v[46:49]
	v_mfma_f32_16x16x32_bf16 v[38:41], v[144:147], v[198:201], v[38:41]
	v_mfma_f32_16x16x32_bf16 v[30:33], v[158:161], v[198:201], v[30:33]
	v_mfma_f32_16x16x32_bf16 v[22:25], v[144:147], v[206:209], v[22:25]
	v_mfma_f32_16x16x32_bf16 v[14:17], v[158:161], v[206:209], v[14:17]
	v_mfma_f32_16x16x32_bf16 v[62:65], v[154:157], v[186:189], v[62:65]
	v_mfma_f32_16x16x32_bf16 v[58:61], v[162:165], v[186:189], v[58:61]
	v_mfma_f32_16x16x32_bf16 v[54:57], v[154:157], v[194:197], v[54:57]
	v_mfma_f32_16x16x32_bf16 v[46:49], v[162:165], v[194:197], v[46:49]
	v_mfma_f32_16x16x32_bf16 v[38:41], v[154:157], v[202:205], v[38:41]
	v_mfma_f32_16x16x32_bf16 v[30:33], v[162:165], v[202:205], v[30:33]
	v_mfma_f32_16x16x32_bf16 v[22:25], v[154:157], v[210:213], v[22:25]
	v_mfma_f32_16x16x32_bf16 v[14:17], v[162:165], v[210:213], v[14:17]
	s_setprio 0
	s_setprio 1
	v_mfma_f32_16x16x32_bf16 v[50:53], v[166:169], v[182:185], v[50:53]
	v_mfma_f32_16x16x32_bf16 v[42:45], v[174:177], v[182:185], v[42:45]
	v_mfma_f32_16x16x32_bf16 v[34:37], v[166:169], v[190:193], v[34:37]
	v_mfma_f32_16x16x32_bf16 v[26:29], v[174:177], v[190:193], v[26:29]
	v_mfma_f32_16x16x32_bf16 v[18:21], v[166:169], v[198:201], v[18:21]
	v_mfma_f32_16x16x32_bf16 v[10:13], v[174:177], v[198:201], v[10:13]
	v_mfma_f32_16x16x32_bf16 v[6:9], v[166:169], v[206:209], v[6:9]
	v_mfma_f32_16x16x32_bf16 v[2:5], v[174:177], v[206:209], v[2:5]
	v_mfma_f32_16x16x32_bf16 v[50:53], v[170:173], v[186:189], v[50:53]
	v_mfma_f32_16x16x32_bf16 v[42:45], v[178:181], v[186:189], v[42:45]
	v_mfma_f32_16x16x32_bf16 v[34:37], v[170:173], v[194:197], v[34:37]
	v_mfma_f32_16x16x32_bf16 v[26:29], v[178:181], v[194:197], v[26:29]
	v_mfma_f32_16x16x32_bf16 v[18:21], v[170:173], v[202:205], v[18:21]
	v_mfma_f32_16x16x32_bf16 v[10:13], v[178:181], v[202:205], v[10:13]
	v_mfma_f32_16x16x32_bf16 v[6:9], v[170:173], v[210:213], v[6:9]
	v_mfma_f32_16x16x32_bf16 v[2:5], v[178:181], v[210:213], v[2:5]
	s_add_i32 s18, s65, 2
	s_add_u32 s16, s16, 0x100
	s_addc_u32 s17, s17, 0
	s_add_u32 s11, s11, 0x100
	s_addc_u32 s64, s64, 0
	s_cmp_ge_i32 s65, s51
	s_mov_b32 s65, s18
	s_setprio 0
	s_barrier
	s_cbranch_scc0 .LBB0_221
	s_and_b64 vcc, exec, s[8:9]
	s_cbranch_vccz .LBB0_224
	s_barrier

.LBB0_398:
	ds_read_b128 v[130:133], v167
	ds_read_b128 v[152:155], v167 offset:1024
	ds_read_b128 v[156:159], v167 offset:2048
	ds_read_b128 v[160:163], v167 offset:3072
	ds_read_b128 v[172:175], v168
	ds_read_b128 v[176:179], v168 offset:1024
	ds_read_b128 v[180:183], v168 offset:2048
	ds_read_b128 v[184:187], v168 offset:3072
	s_add_u32 s50, s86, 0xfffc0080
	s_addc_u32 s51, s87, -1
	s_cmp_eq_u32 s49, 12
	s_cselect_b32 s91, s7, s51
	s_cselect_b32 s90, s23, s50
	s_cselect_b32 s89, s35, s48
	s_cselect_b32 s88, s46, s47
	v_lshl_add_u64 v[220:221], s[86:87], 0, v[144:145]
	s_add_i32 m0, s75, 0xc000
	ds_read_b128 v[188:191], v169
	ds_read_b128 v[192:195], v169 offset:1024
	ds_read_b128 v[196:199], v169 offset:2048
	ds_read_b128 v[200:203], v169 offset:3072
	ds_read_b128 v[204:207], v169 offset:4096
	ds_read_b128 v[208:211], v169 offset:5120
	ds_read_b128 v[212:215], v169 offset:6144
	ds_read_b128 v[216:219], v169 offset:7168
	global_load_lds_dwordx4 v[220:221], off
	v_lshl_add_u64 v[220:221], s[86:87], 0, v[146:147]
	s_add_i32 m0, s75, 0xe000
	s_nop 0
	global_load_lds_dwordx4 v[220:221], off
	s_waitcnt vmcnt(8)
	s_waitcnt lgkmcnt(0)
	s_barrier
	s_setprio 1
	s_waitcnt lgkmcnt(0)
	v_mfma_f32_16x16x32_bf16 v[126:129], v[130:133], v[188:191], v[126:129]
	v_mfma_f32_16x16x32_bf16 v[122:125], v[156:159], v[188:191], v[122:125]
	v_mfma_f32_16x16x32_bf16 v[110:113], v[130:133], v[196:199], v[110:113]
	v_mfma_f32_16x16x32_bf16 v[106:109], v[156:159], v[196:199], v[106:109]
	v_mfma_f32_16x16x32_bf16 v[94:97], v[130:133], v[204:207], v[94:97]
	v_mfma_f32_16x16x32_bf16 v[90:93], v[156:159], v[204:207], v[90:93]
	v_mfma_f32_16x16x32_bf16 v[78:81], v[130:133], v[212:215], v[78:81]
	v_mfma_f32_16x16x32_bf16 v[74:77], v[156:159], v[212:215], v[74:77]
	v_mfma_f32_16x16x32_bf16 v[126:129], v[152:155], v[192:195], v[126:129]
	v_mfma_f32_16x16x32_bf16 v[122:125], v[160:163], v[192:195], v[122:125]
	v_mfma_f32_16x16x32_bf16 v[110:113], v[152:155], v[200:203], v[110:113]
	v_mfma_f32_16x16x32_bf16 v[106:109], v[160:163], v[200:203], v[106:109]
	v_mfma_f32_16x16x32_bf16 v[94:97], v[152:155], v[208:211], v[94:97]
	v_mfma_f32_16x16x32_bf16 v[90:93], v[160:163], v[208:211], v[90:93]
	v_mfma_f32_16x16x32_bf16 v[78:81], v[152:155], v[216:219], v[78:81]
	v_mfma_f32_16x16x32_bf16 v[74:77], v[160:163], v[216:219], v[74:77]
	s_setprio 0
	s_setprio 1
	v_mfma_f32_16x16x32_bf16 v[118:121], v[172:175], v[188:191], v[118:121]
	v_mfma_f32_16x16x32_bf16 v[114:117], v[180:183], v[188:191], v[114:117]
	v_mfma_f32_16x16x32_bf16 v[102:105], v[172:175], v[196:199], v[102:105]
	v_mfma_f32_16x16x32_bf16 v[98:101], v[180:183], v[196:199], v[98:101]
	v_mfma_f32_16x16x32_bf16 v[86:89], v[172:175], v[204:207], v[86:89]
	v_mfma_f32_16x16x32_bf16 v[82:85], v[180:183], v[204:207], v[82:85]
	v_mfma_f32_16x16x32_bf16 v[70:73], v[172:175], v[212:215], v[70:73]
	v_mfma_f32_16x16x32_bf16 v[66:69], v[180:183], v[212:215], v[66:69]
	v_mfma_f32_16x16x32_bf16 v[118:121], v[176:179], v[192:195], v[118:121]
	v_mfma_f32_16x16x32_bf16 v[114:117], v[184:187], v[192:195], v[114:117]
	v_mfma_f32_16x16x32_bf16 v[102:105], v[176:179], v[200:203], v[102:105]
	v_mfma_f32_16x16x32_bf16 v[98:101], v[184:187], v[200:203], v[98:101]
	v_mfma_f32_16x16x32_bf16 v[86:89], v[176:179], v[208:211], v[86:89]
	v_mfma_f32_16x16x32_bf16 v[82:85], v[184:187], v[208:211], v[82:85]
	v_mfma_f32_16x16x32_bf16 v[70:73], v[176:179], v[216:219], v[70:73]
	v_mfma_f32_16x16x32_bf16 v[66:69], v[184:187], v[216:219], v[66:69]
	s_setprio 0
	s_barrier
	s_add_i32 s50, s68, s74
	v_lshl_add_u64 v[220:221], s[88:89], 0, v[136:137]
	s_mov_b32 m0, s50
	ds_read_b128 v[188:191], v169 offset:16384
	ds_read_b128 v[192:195], v169 offset:17408
	ds_read_b128 v[196:199], v169 offset:18432
	ds_read_b128 v[200:203], v169 offset:19456
	ds_read_b128 v[204:207], v169 offset:20480
	ds_read_b128 v[208:211], v169 offset:21504
	ds_read_b128 v[212:215], v169 offset:22528
	ds_read_b128 v[216:219], v169 offset:23552
	global_load_lds_dwordx4 v[220:221], off
	s_add_i32 m0, s50, 0x2000
	s_add_u32 s50, s88, 0x40000
	v_lshl_add_u64 v[222:223], s[88:89], 0, v[140:141]
	s_addc_u32 s51, s89, 0
	s_add_i32 s85, s28, s74
	global_load_lds_dwordx4 v[222:223], off
	v_lshl_add_u64 v[224:225], s[50:51], 0, v[136:137]
	s_mov_b32 m0, s85
	v_lshl_add_u64 v[226:227], s[90:91], 0, v[138:139]
	global_load_lds_dwordx4 v[224:225], off
	v_lshl_add_u64 v[224:225], s[50:51], 0, v[140:141]
	s_add_i32 m0, s85, 0x2000
	s_nop 0
	global_load_lds_dwordx4 v[224:225], off
	v_lshl_add_u64 v[224:225], s[90:91], 0, v[134:135]
	s_mov_b32 m0, s75
	s_nop 0
	global_load_lds_dwordx4 v[224:225], off
	s_mov_b32 m0, s76
	s_nop 0
	global_load_lds_dwordx4 v[226:227], off
	s_waitcnt vmcnt(8)
	s_waitcnt lgkmcnt(0)
	s_barrier
	s_setprio 1
	s_waitcnt lgkmcnt(0)
	v_mfma_f32_16x16x32_bf16 v[62:65], v[130:133], v[188:191], v[62:65]
	v_mfma_f32_16x16x32_bf16 v[58:61], v[156:159], v[188:191], v[58:61]
	v_mfma_f32_16x16x32_bf16 v[46:49], v[130:133], v[196:199], v[46:49]
	v_mfma_f32_16x16x32_bf16 v[42:45], v[156:159], v[196:199], v[42:45]
	v_mfma_f32_16x16x32_bf16 v[30:33], v[130:133], v[204:207], v[30:33]
	v_mfma_f32_16x16x32_bf16 v[26:29], v[156:159], v[204:207], v[26:29]
	v_mfma_f32_16x16x32_bf16 v[14:17], v[130:133], v[212:215], v[14:17]
	v_mfma_f32_16x16x32_bf16 v[10:13], v[156:159], v[212:215], v[10:13]
	v_mfma_f32_16x16x32_bf16 v[62:65], v[152:155], v[192:195], v[62:65]
	v_mfma_f32_16x16x32_bf16 v[58:61], v[160:163], v[192:195], v[58:61]
	v_mfma_f32_16x16x32_bf16 v[46:49], v[152:155], v[200:203], v[46:49]
	v_mfma_f32_16x16x32_bf16 v[42:45], v[160:163], v[200:203], v[42:45]
	v_mfma_f32_16x16x32_bf16 v[30:33], v[152:155], v[208:211], v[30:33]
	v_mfma_f32_16x16x32_bf16 v[26:29], v[160:163], v[208:211], v[26:29]
	v_mfma_f32_16x16x32_bf16 v[14:17], v[152:155], v[216:219], v[14:17]
	v_mfma_f32_16x16x32_bf16 v[10:13], v[160:163], v[216:219], v[10:13]
	s_setprio 0
	s_setprio 1
	v_mfma_f32_16x16x32_bf16 v[54:57], v[172:175], v[188:191], v[54:57]
	v_mfma_f32_16x16x32_bf16 v[50:53], v[180:183], v[188:191], v[50:53]
	v_mfma_f32_16x16x32_bf16 v[38:41], v[172:175], v[196:199], v[38:41]
	v_mfma_f32_16x16x32_bf16 v[34:37], v[180:183], v[196:199], v[34:37]
	v_mfma_f32_16x16x32_bf16 v[22:25], v[172:175], v[204:207], v[22:25]
	v_mfma_f32_16x16x32_bf16 v[18:21], v[180:183], v[204:207], v[18:21]
	v_mfma_f32_16x16x32_bf16 v[6:9], v[172:175], v[212:215], v[6:9]
	v_mfma_f32_16x16x32_bf16 v[2:5], v[180:183], v[212:215], v[2:5]
	v_mfma_f32_16x16x32_bf16 v[54:57], v[176:179], v[192:195], v[54:57]
	v_mfma_f32_16x16x32_bf16 v[50:53], v[184:187], v[192:195], v[50:53]
	v_mfma_f32_16x16x32_bf16 v[38:41], v[176:179], v[200:203], v[38:41]
	v_mfma_f32_16x16x32_bf16 v[34:37], v[184:187], v[200:203], v[34:37]
	v_mfma_f32_16x16x32_bf16 v[22:25], v[176:179], v[208:211], v[22:25]
	v_mfma_f32_16x16x32_bf16 v[18:21], v[184:187], v[208:211], v[18:21]
	v_mfma_f32_16x16x32_bf16 v[6:9], v[176:179], v[216:219], v[6:9]
	v_mfma_f32_16x16x32_bf16 v[2:5], v[184:187], v[216:219], v[2:5]
	s_setprio 0
	s_barrier
	s_add_i32 s85, 0, 0x18000
	v_add_u32_e32 v142, s85, v165
	s_add_i32 s92, 0, 0x1c000
	ds_read_b128 v[130:133], v142
	ds_read_b128 v[152:155], v142 offset:1024
	ds_read_b128 v[156:159], v142 offset:2048
	ds_read_b128 v[160:163], v142 offset:3072
	v_add_u32_e32 v142, s92, v165
	ds_read_b128 v[172:175], v142
	ds_read_b128 v[176:179], v142 offset:1024
	ds_read_b128 v[180:183], v142 offset:2048
	ds_read_b128 v[184:187], v142 offset:3072
	s_add_u32 s50, s90, 0x40000
	s_addc_u32 s51, s91, 0
	s_mov_b32 m0, s77
	v_lshl_add_u64 v[228:229], s[50:51], 0, v[134:135]
	ds_read_b128 v[188:191], v169 offset:32768
	ds_read_b128 v[192:195], v169 offset:33792
	ds_read_b128 v[196:199], v169 offset:34816
	ds_read_b128 v[200:203], v169 offset:35840
	ds_read_b128 v[204:207], v169 offset:36864
	ds_read_b128 v[208:211], v169 offset:37888
	ds_read_b128 v[212:215], v169 offset:38912
	ds_read_b128 v[216:219], v169 offset:39936
	global_load_lds_dwordx4 v[228:229], off
	v_lshl_add_u64 v[228:229], s[50:51], 0, v[138:139]
	s_mov_b32 m0, s78
	s_nop 0
	global_load_lds_dwordx4 v[228:229], off
	s_waitcnt vmcnt(8)
	s_waitcnt lgkmcnt(0)
	s_barrier
	s_setprio 1
	s_waitcnt lgkmcnt(0)
	v_mfma_f32_16x16x32_bf16 v[126:129], v[130:133], v[188:191], v[126:129]
	v_mfma_f32_16x16x32_bf16 v[122:125], v[156:159], v[188:191], v[122:125]
	v_mfma_f32_16x16x32_bf16 v[110:113], v[130:133], v[196:199], v[110:113]
	v_mfma_f32_16x16x32_bf16 v[106:109], v[156:159], v[196:199], v[106:109]
	v_mfma_f32_16x16x32_bf16 v[94:97], v[130:133], v[204:207], v[94:97]
	v_mfma_f32_16x16x32_bf16 v[90:93], v[156:159], v[204:207], v[90:93]
	v_mfma_f32_16x16x32_bf16 v[78:81], v[130:133], v[212:215], v[78:81]
	v_mfma_f32_16x16x32_bf16 v[74:77], v[156:159], v[212:215], v[74:77]
	v_mfma_f32_16x16x32_bf16 v[126:129], v[152:155], v[192:195], v[126:129]
	v_mfma_f32_16x16x32_bf16 v[122:125], v[160:163], v[192:195], v[122:125]
	v_mfma_f32_16x16x32_bf16 v[110:113], v[152:155], v[200:203], v[110:113]
	v_mfma_f32_16x16x32_bf16 v[106:109], v[160:163], v[200:203], v[106:109]
	v_mfma_f32_16x16x32_bf16 v[94:97], v[152:155], v[208:211], v[94:97]
	v_mfma_f32_16x16x32_bf16 v[90:93], v[160:163], v[208:211], v[90:93]
	v_mfma_f32_16x16x32_bf16 v[78:81], v[152:155], v[216:219], v[78:81]
	v_mfma_f32_16x16x32_bf16 v[74:77], v[160:163], v[216:219], v[74:77]
	s_setprio 0
	s_setprio 1
	v_mfma_f32_16x16x32_bf16 v[118:121], v[172:175], v[188:191], v[118:121]
	v_mfma_f32_16x16x32_bf16 v[114:117], v[180:183], v[188:191], v[114:117]
	v_mfma_f32_16x16x32_bf16 v[102:105], v[172:175], v[196:199], v[102:105]
	v_mfma_f32_16x16x32_bf16 v[98:101], v[180:183], v[196:199], v[98:101]
	v_mfma_f32_16x16x32_bf16 v[86:89], v[172:175], v[204:207], v[86:89]
	v_mfma_f32_16x16x32_bf16 v[82:85], v[180:183], v[204:207], v[82:85]
	v_mfma_f32_16x16x32_bf16 v[70:73], v[172:175], v[212:215], v[70:73]
	v_mfma_f32_16x16x32_bf16 v[66:69], v[180:183], v[212:215], v[66:69]
	v_mfma_f32_16x16x32_bf16 v[118:121], v[176:179], v[192:195], v[118:121]
	v_mfma_f32_16x16x32_bf16 v[114:117], v[184:187], v[192:195], v[114:117]
	v_mfma_f32_16x16x32_bf16 v[102:105], v[176:179], v[200:203], v[102:105]
	v_mfma_f32_16x16x32_bf16 v[98:101], v[184:187], v[200:203], v[98:101]
	v_mfma_f32_16x16x32_bf16 v[86:89], v[176:179], v[208:211], v[86:89]
	v_mfma_f32_16x16x32_bf16 v[82:85], v[184:187], v[208:211], v[82:85]
	v_mfma_f32_16x16x32_bf16 v[70:73], v[176:179], v[216:219], v[70:73]
	v_mfma_f32_16x16x32_bf16 v[66:69], v[184:187], v[216:219], v[66:69]
	s_setprio 0
	s_barrier
	s_add_i32 s50, s85, s74
	v_lshl_add_u64 v[220:221], v[220:221], 0, s[38:39]
	s_mov_b32 m0, s50
	ds_read_b128 v[188:191], v169 offset:49152
	ds_read_b128 v[192:195], v169 offset:50176
	ds_read_b128 v[196:199], v169 offset:51200
	ds_read_b128 v[200:203], v169 offset:52224
	ds_read_b128 v[204:207], v169 offset:53248
	ds_read_b128 v[208:211], v169 offset:54272
	ds_read_b128 v[212:215], v169 offset:55296
	ds_read_b128 v[216:219], v169 offset:56320
	global_load_lds_dwordx4 v[220:221], off
	s_add_i32 m0, s50, 0x2000
	s_add_u32 s50, s88, 0x40080
	v_lshl_add_u64 v[220:221], v[222:223], 0, s[38:39]
	s_addc_u32 s51, s89, 0
	s_add_i32 s85, s92, s74
	global_load_lds_dwordx4 v[220:221], off
	v_lshl_add_u64 v[220:221], s[50:51], 0, v[136:137]
	s_mov_b32 m0, s85
	s_nop 0
	global_load_lds_dwordx4 v[220:221], off
	v_lshl_add_u64 v[220:221], s[50:51], 0, v[140:141]
	s_add_i32 m0, s85, 0x2000
	s_nop 0
	global_load_lds_dwordx4 v[220:221], off
	v_lshl_add_u64 v[220:221], v[224:225], 0, s[38:39]
	s_mov_b32 m0, s25
	s_nop 0
	global_load_lds_dwordx4 v[220:221], off
	v_lshl_add_u64 v[220:221], v[226:227], 0, s[38:39]
	s_mov_b32 m0, s69
	s_nop 0
	global_load_lds_dwordx4 v[220:221], off
	s_waitcnt vmcnt(8)
	s_waitcnt lgkmcnt(0)
	s_barrier
	s_setprio 1
	s_waitcnt lgkmcnt(0)
	v_mfma_f32_16x16x32_bf16 v[62:65], v[130:133], v[188:191], v[62:65]
	v_mfma_f32_16x16x32_bf16 v[58:61], v[156:159], v[188:191], v[58:61]
	v_mfma_f32_16x16x32_bf16 v[46:49], v[130:133], v[196:199], v[46:49]
	v_mfma_f32_16x16x32_bf16 v[42:45], v[156:159], v[196:199], v[42:45]
	v_mfma_f32_16x16x32_bf16 v[30:33], v[130:133], v[204:207], v[30:33]
	v_mfma_f32_16x16x32_bf16 v[26:29], v[156:159], v[204:207], v[26:29]
	v_mfma_f32_16x16x32_bf16 v[14:17], v[130:133], v[212:215], v[14:17]
	v_mfma_f32_16x16x32_bf16 v[10:13], v[156:159], v[212:215], v[10:13]
	v_mfma_f32_16x16x32_bf16 v[62:65], v[152:155], v[192:195], v[62:65]
	v_mfma_f32_16x16x32_bf16 v[58:61], v[160:163], v[192:195], v[58:61]
	v_mfma_f32_16x16x32_bf16 v[46:49], v[152:155], v[200:203], v[46:49]
	v_mfma_f32_16x16x32_bf16 v[42:45], v[160:163], v[200:203], v[42:45]
	v_mfma_f32_16x16x32_bf16 v[30:33], v[152:155], v[208:211], v[30:33]
	v_mfma_f32_16x16x32_bf16 v[26:29], v[160:163], v[208:211], v[26:29]
	v_mfma_f32_16x16x32_bf16 v[14:17], v[152:155], v[216:219], v[14:17]
	v_mfma_f32_16x16x32_bf16 v[10:13], v[160:163], v[216:219], v[10:13]
	s_setprio 0
	s_setprio 1
	v_mfma_f32_16x16x32_bf16 v[54:57], v[172:175], v[188:191], v[54:57]
	v_mfma_f32_16x16x32_bf16 v[50:53], v[180:183], v[188:191], v[50:53]
	v_mfma_f32_16x16x32_bf16 v[38:41], v[172:175], v[196:199], v[38:41]
	v_mfma_f32_16x16x32_bf16 v[34:37], v[180:183], v[196:199], v[34:37]
	v_mfma_f32_16x16x32_bf16 v[22:25], v[172:175], v[204:207], v[22:25]
	v_mfma_f32_16x16x32_bf16 v[18:21], v[180:183], v[204:207], v[18:21]
	v_mfma_f32_16x16x32_bf16 v[6:9], v[172:175], v[212:215], v[6:9]
	v_mfma_f32_16x16x32_bf16 v[2:5], v[180:183], v[212:215], v[2:5]
	v_mfma_f32_16x16x32_bf16 v[54:57], v[176:179], v[192:195], v[54:57]
	v_mfma_f32_16x16x32_bf16 v[50:53], v[184:187], v[192:195], v[50:53]
	v_mfma_f32_16x16x32_bf16 v[38:41], v[176:179], v[200:203], v[38:41]
	v_mfma_f32_16x16x32_bf16 v[34:37], v[184:187], v[200:203], v[34:37]
	v_mfma_f32_16x16x32_bf16 v[22:25], v[176:179], v[208:211], v[22:25]
	v_mfma_f32_16x16x32_bf16 v[18:21], v[184:187], v[208:211], v[18:21]
	v_mfma_f32_16x16x32_bf16 v[6:9], v[176:179], v[216:219], v[6:9]
	v_mfma_f32_16x16x32_bf16 v[2:5], v[184:187], v[216:219], v[2:5]
	s_add_i32 s49, s49, 2
	s_add_u32 s86, s86, 0x100
	s_addc_u32 s87, s87, 0
	s_add_u32 s47, s47, 0x100
	s_addc_u32 s48, s48, 0
	s_cmp_gt_u32 s49, 13
	s_setprio 0
	s_barrier
	s_cbranch_scc0 .LBB0_398
	s_and_b64 vcc, exec, s[44:45]
	s_cbranch_vccz .LBB0_401
	s_barrier

.LBB0_1522:
	ds_read_b128 v[144:147], v150
	ds_read_b128 v[154:157], v150 offset:1024
	ds_read_b128 v[158:161], v150 offset:2048
	ds_read_b128 v[162:165], v150 offset:3072
	ds_read_b128 v[166:169], v151
	ds_read_b128 v[170:173], v151 offset:1024
	ds_read_b128 v[174:177], v151 offset:2048
	ds_read_b128 v[178:181], v151 offset:3072
	s_add_u32 s19, s34, 0xfffc0080
	s_addc_u32 s36, s35, -1
	s_cmp_eq_u32 s78, s17
	s_cselect_b32 s39, s23, s36
	s_cselect_b32 s38, s22, s19
	s_cselect_b32 s37, s31, s15
	s_cselect_b32 s36, s30, s13
	v_lshl_add_u64 v[214:215], s[34:35], 0, v[138:139]
	s_add_i32 m0, s21, 0xc000
	ds_read_b128 v[182:185], v152
	ds_read_b128 v[186:189], v152 offset:1024
	ds_read_b128 v[190:193], v152 offset:2048
	ds_read_b128 v[194:197], v152 offset:3072
	ds_read_b128 v[198:201], v152 offset:4096
	ds_read_b128 v[202:205], v152 offset:5120
	ds_read_b128 v[206:209], v152 offset:6144
	ds_read_b128 v[210:213], v152 offset:7168
	global_load_lds_dwordx4 v[214:215], off
	v_lshl_add_u64 v[214:215], s[34:35], 0, v[140:141]
	s_add_i32 m0, s21, 0xe000
	s_nop 0
	global_load_lds_dwordx4 v[214:215], off
	s_waitcnt vmcnt(8)
	s_waitcnt lgkmcnt(0)
	s_barrier
	s_setprio 1
	s_waitcnt lgkmcnt(0)
	v_mfma_f32_16x16x32_bf16 v[126:129], v[144:147], v[182:185], v[126:129]
	v_mfma_f32_16x16x32_bf16 v[122:125], v[158:161], v[182:185], v[122:125]
	v_mfma_f32_16x16x32_bf16 v[118:121], v[144:147], v[190:193], v[118:121]
	v_mfma_f32_16x16x32_bf16 v[110:113], v[158:161], v[190:193], v[110:113]
	v_mfma_f32_16x16x32_bf16 v[102:105], v[144:147], v[198:201], v[102:105]
	v_mfma_f32_16x16x32_bf16 v[94:97], v[158:161], v[198:201], v[94:97]
	v_mfma_f32_16x16x32_bf16 v[86:89], v[144:147], v[206:209], v[86:89]
	v_mfma_f32_16x16x32_bf16 v[78:81], v[158:161], v[206:209], v[78:81]
	v_mfma_f32_16x16x32_bf16 v[126:129], v[154:157], v[186:189], v[126:129]
	v_mfma_f32_16x16x32_bf16 v[122:125], v[162:165], v[186:189], v[122:125]
	v_mfma_f32_16x16x32_bf16 v[118:121], v[154:157], v[194:197], v[118:121]
	v_mfma_f32_16x16x32_bf16 v[110:113], v[162:165], v[194:197], v[110:113]
	v_mfma_f32_16x16x32_bf16 v[102:105], v[154:157], v[202:205], v[102:105]
	v_mfma_f32_16x16x32_bf16 v[94:97], v[162:165], v[202:205], v[94:97]
	v_mfma_f32_16x16x32_bf16 v[86:89], v[154:157], v[210:213], v[86:89]
	v_mfma_f32_16x16x32_bf16 v[78:81], v[162:165], v[210:213], v[78:81]
	s_setprio 0
	s_setprio 1
	v_mfma_f32_16x16x32_bf16 v[114:117], v[166:169], v[182:185], v[114:117]
	v_mfma_f32_16x16x32_bf16 v[106:109], v[174:177], v[182:185], v[106:109]
	v_mfma_f32_16x16x32_bf16 v[98:101], v[166:169], v[190:193], v[98:101]
	v_mfma_f32_16x16x32_bf16 v[90:93], v[174:177], v[190:193], v[90:93]
	v_mfma_f32_16x16x32_bf16 v[82:85], v[166:169], v[198:201], v[82:85]
	v_mfma_f32_16x16x32_bf16 v[74:77], v[174:177], v[198:201], v[74:77]
	v_mfma_f32_16x16x32_bf16 v[70:73], v[166:169], v[206:209], v[70:73]
	v_mfma_f32_16x16x32_bf16 v[66:69], v[174:177], v[206:209], v[66:69]
	v_mfma_f32_16x16x32_bf16 v[114:117], v[170:173], v[186:189], v[114:117]
	v_mfma_f32_16x16x32_bf16 v[106:109], v[178:181], v[186:189], v[106:109]
	v_mfma_f32_16x16x32_bf16 v[98:101], v[170:173], v[194:197], v[98:101]
	v_mfma_f32_16x16x32_bf16 v[90:93], v[178:181], v[194:197], v[90:93]
	v_mfma_f32_16x16x32_bf16 v[82:85], v[170:173], v[202:205], v[82:85]
	v_mfma_f32_16x16x32_bf16 v[74:77], v[178:181], v[202:205], v[74:77]
	v_mfma_f32_16x16x32_bf16 v[70:73], v[170:173], v[210:213], v[70:73]
	v_mfma_f32_16x16x32_bf16 v[66:69], v[178:181], v[210:213], v[66:69]
	s_setprio 0
	s_barrier
	s_add_i32 s19, s55, s41
	v_lshl_add_u64 v[214:215], s[36:37], 0, v[132:133]
	s_mov_b32 m0, s19
	ds_read_b128 v[182:185], v152 offset:16384
	ds_read_b128 v[186:189], v152 offset:17408
	ds_read_b128 v[190:193], v152 offset:18432
	ds_read_b128 v[194:197], v152 offset:19456
	ds_read_b128 v[198:201], v152 offset:20480
	ds_read_b128 v[202:205], v152 offset:21504
	ds_read_b128 v[206:209], v152 offset:22528
	ds_read_b128 v[210:213], v152 offset:23552
	global_load_lds_dwordx4 v[214:215], off
	s_add_i32 m0, s19, 0x2000
	s_add_u32 s80, s36, 0x40000
	v_lshl_add_u64 v[216:217], s[36:37], 0, v[136:137]
	s_addc_u32 s81, s37, 0
	s_add_i32 s19, s56, s41
	global_load_lds_dwordx4 v[216:217], off
	v_lshl_add_u64 v[218:219], s[80:81], 0, v[132:133]
	s_mov_b32 m0, s19
	v_lshl_add_u64 v[220:221], s[38:39], 0, v[134:135]
	global_load_lds_dwordx4 v[218:219], off
	v_lshl_add_u64 v[218:219], s[80:81], 0, v[136:137]
	s_add_i32 m0, s19, 0x2000
	s_nop 0
	global_load_lds_dwordx4 v[218:219], off
	v_lshl_add_u64 v[218:219], s[38:39], 0, v[130:131]
	s_mov_b32 m0, s21
	s_nop 0
	global_load_lds_dwordx4 v[218:219], off
	s_mov_b32 m0, s42
	s_nop 0
	global_load_lds_dwordx4 v[220:221], off
	s_waitcnt vmcnt(8)
	s_waitcnt lgkmcnt(0)
	s_barrier
	s_setprio 1
	s_waitcnt lgkmcnt(0)
	v_mfma_f32_16x16x32_bf16 v[62:65], v[144:147], v[182:185], v[62:65]
	v_mfma_f32_16x16x32_bf16 v[58:61], v[158:161], v[182:185], v[58:61]
	v_mfma_f32_16x16x32_bf16 v[54:57], v[144:147], v[190:193], v[54:57]
	v_mfma_f32_16x16x32_bf16 v[46:49], v[158:161], v[190:193], v[46:49]
	v_mfma_f32_16x16x32_bf16 v[38:41], v[144:147], v[198:201], v[38:41]
	v_mfma_f32_16x16x32_bf16 v[30:33], v[158:161], v[198:201], v[30:33]
	v_mfma_f32_16x16x32_bf16 v[22:25], v[144:147], v[206:209], v[22:25]
	v_mfma_f32_16x16x32_bf16 v[14:17], v[158:161], v[206:209], v[14:17]
	v_mfma_f32_16x16x32_bf16 v[62:65], v[154:157], v[186:189], v[62:65]
	v_mfma_f32_16x16x32_bf16 v[58:61], v[162:165], v[186:189], v[58:61]
	v_mfma_f32_16x16x32_bf16 v[54:57], v[154:157], v[194:197], v[54:57]
	v_mfma_f32_16x16x32_bf16 v[46:49], v[162:165], v[194:197], v[46:49]
	v_mfma_f32_16x16x32_bf16 v[38:41], v[154:157], v[202:205], v[38:41]
	v_mfma_f32_16x16x32_bf16 v[30:33], v[162:165], v[202:205], v[30:33]
	v_mfma_f32_16x16x32_bf16 v[22:25], v[154:157], v[210:213], v[22:25]
	v_mfma_f32_16x16x32_bf16 v[14:17], v[162:165], v[210:213], v[14:17]
	s_setprio 0
	s_setprio 1
	v_mfma_f32_16x16x32_bf16 v[50:53], v[166:169], v[182:185], v[50:53]
	v_mfma_f32_16x16x32_bf16 v[42:45], v[174:177], v[182:185], v[42:45]
	v_mfma_f32_16x16x32_bf16 v[34:37], v[166:169], v[190:193], v[34:37]
	v_mfma_f32_16x16x32_bf16 v[26:29], v[174:177], v[190:193], v[26:29]
	v_mfma_f32_16x16x32_bf16 v[18:21], v[166:169], v[198:201], v[18:21]
	v_mfma_f32_16x16x32_bf16 v[10:13], v[174:177], v[198:201], v[10:13]
	v_mfma_f32_16x16x32_bf16 v[6:9], v[166:169], v[206:209], v[6:9]
	v_mfma_f32_16x16x32_bf16 v[2:5], v[174:177], v[206:209], v[2:5]
	v_mfma_f32_16x16x32_bf16 v[50:53], v[170:173], v[186:189], v[50:53]
	v_mfma_f32_16x16x32_bf16 v[42:45], v[178:181], v[186:189], v[42:45]
	v_mfma_f32_16x16x32_bf16 v[34:37], v[170:173], v[194:197], v[34:37]
	v_mfma_f32_16x16x32_bf16 v[26:29], v[178:181], v[194:197], v[26:29]
	v_mfma_f32_16x16x32_bf16 v[18:21], v[170:173], v[202:205], v[18:21]
	v_mfma_f32_16x16x32_bf16 v[10:13], v[178:181], v[202:205], v[10:13]
	v_mfma_f32_16x16x32_bf16 v[6:9], v[170:173], v[210:213], v[6:9]
	v_mfma_f32_16x16x32_bf16 v[2:5], v[178:181], v[210:213], v[2:5]
	s_setprio 0
	s_barrier
	s_add_i32 s19, 0, 0x18000
	v_add_u32_e32 v153, s19, v148
	s_add_i32 s79, 0, 0x1c000
	ds_read_b128 v[144:147], v153
	ds_read_b128 v[154:157], v153 offset:1024
	ds_read_b128 v[158:161], v153 offset:2048
	ds_read_b128 v[162:165], v153 offset:3072
	v_add_u32_e32 v153, s79, v148
	ds_read_b128 v[166:169], v153
	ds_read_b128 v[170:173], v153 offset:1024
	ds_read_b128 v[174:177], v153 offset:2048
	ds_read_b128 v[178:181], v153 offset:3072
	s_add_u32 s38, s38, 0x40000
	s_addc_u32 s39, s39, 0
	s_mov_b32 m0, s43
	v_lshl_add_u64 v[222:223], s[38:39], 0, v[130:131]
	ds_read_b128 v[182:185], v152 offset:32768
	ds_read_b128 v[186:189], v152 offset:33792
	ds_read_b128 v[190:193], v152 offset:34816
	ds_read_b128 v[194:197], v152 offset:35840
	ds_read_b128 v[198:201], v152 offset:36864
	ds_read_b128 v[202:205], v152 offset:37888
	ds_read_b128 v[206:209], v152 offset:38912
	ds_read_b128 v[210:213], v152 offset:39936
	global_load_lds_dwordx4 v[222:223], off
	v_lshl_add_u64 v[222:223], s[38:39], 0, v[134:135]
	s_mov_b32 m0, s44
	s_nop 0
	global_load_lds_dwordx4 v[222:223], off
	s_waitcnt vmcnt(8)
	s_waitcnt lgkmcnt(0)
	s_barrier
	s_setprio 1
	s_waitcnt lgkmcnt(0)
	v_mfma_f32_16x16x32_bf16 v[126:129], v[144:147], v[182:185], v[126:129]
	v_mfma_f32_16x16x32_bf16 v[122:125], v[158:161], v[182:185], v[122:125]
	v_mfma_f32_16x16x32_bf16 v[118:121], v[144:147], v[190:193], v[118:121]
	v_mfma_f32_16x16x32_bf16 v[110:113], v[158:161], v[190:193], v[110:113]
	v_mfma_f32_16x16x32_bf16 v[102:105], v[144:147], v[198:201], v[102:105]
	v_mfma_f32_16x16x32_bf16 v[94:97], v[158:161], v[198:201], v[94:97]
	v_mfma_f32_16x16x32_bf16 v[86:89], v[144:147], v[206:209], v[86:89]
	v_mfma_f32_16x16x32_bf16 v[78:81], v[158:161], v[206:209], v[78:81]
	v_mfma_f32_16x16x32_bf16 v[126:129], v[154:157], v[186:189], v[126:129]
	v_mfma_f32_16x16x32_bf16 v[122:125], v[162:165], v[186:189], v[122:125]
	v_mfma_f32_16x16x32_bf16 v[118:121], v[154:157], v[194:197], v[118:121]
	v_mfma_f32_16x16x32_bf16 v[110:113], v[162:165], v[194:197], v[110:113]
	v_mfma_f32_16x16x32_bf16 v[102:105], v[154:157], v[202:205], v[102:105]
	v_mfma_f32_16x16x32_bf16 v[94:97], v[162:165], v[202:205], v[94:97]
	v_mfma_f32_16x16x32_bf16 v[86:89], v[154:157], v[210:213], v[86:89]
	v_mfma_f32_16x16x32_bf16 v[78:81], v[162:165], v[210:213], v[78:81]
	s_setprio 0
	s_setprio 1
	v_mfma_f32_16x16x32_bf16 v[114:117], v[166:169], v[182:185], v[114:117]
	v_mfma_f32_16x16x32_bf16 v[106:109], v[174:177], v[182:185], v[106:109]
	v_mfma_f32_16x16x32_bf16 v[98:101], v[166:169], v[190:193], v[98:101]
	v_mfma_f32_16x16x32_bf16 v[90:93], v[174:177], v[190:193], v[90:93]
	v_mfma_f32_16x16x32_bf16 v[82:85], v[166:169], v[198:201], v[82:85]
	v_mfma_f32_16x16x32_bf16 v[74:77], v[174:177], v[198:201], v[74:77]
	v_mfma_f32_16x16x32_bf16 v[70:73], v[166:169], v[206:209], v[70:73]
	v_mfma_f32_16x16x32_bf16 v[66:69], v[174:177], v[206:209], v[66:69]
	v_mfma_f32_16x16x32_bf16 v[114:117], v[170:173], v[186:189], v[114:117]
	v_mfma_f32_16x16x32_bf16 v[106:109], v[178:181], v[186:189], v[106:109]
	v_mfma_f32_16x16x32_bf16 v[98:101], v[170:173], v[194:197], v[98:101]
	v_mfma_f32_16x16x32_bf16 v[90:93], v[178:181], v[194:197], v[90:93]
	v_mfma_f32_16x16x32_bf16 v[82:85], v[170:173], v[202:205], v[82:85]
	v_mfma_f32_16x16x32_bf16 v[74:77], v[178:181], v[202:205], v[74:77]
	v_mfma_f32_16x16x32_bf16 v[70:73], v[170:173], v[210:213], v[70:73]
	v_mfma_f32_16x16x32_bf16 v[66:69], v[178:181], v[210:213], v[66:69]
	s_setprio 0
	s_barrier
	s_add_i32 s19, s19, s41
	v_lshl_add_u64 v[214:215], v[214:215], 0, s[6:7]
	s_mov_b32 m0, s19
	ds_read_b128 v[182:185], v152 offset:49152
	ds_read_b128 v[186:189], v152 offset:50176
	ds_read_b128 v[190:193], v152 offset:51200
	ds_read_b128 v[194:197], v152 offset:52224
	ds_read_b128 v[198:201], v152 offset:53248
	ds_read_b128 v[202:205], v152 offset:54272
	ds_read_b128 v[206:209], v152 offset:55296
	ds_read_b128 v[210:213], v152 offset:56320
	global_load_lds_dwordx4 v[214:215], off
	s_add_i32 m0, s19, 0x2000
	s_add_u32 s36, s36, 0x40080
	v_lshl_add_u64 v[214:215], v[216:217], 0, s[6:7]
	s_addc_u32 s37, s37, 0
	s_add_i32 s19, s79, s41
	global_load_lds_dwordx4 v[214:215], off
	v_lshl_add_u64 v[214:215], s[36:37], 0, v[132:133]
	s_mov_b32 m0, s19
	s_nop 0
	global_load_lds_dwordx4 v[214:215], off
	v_lshl_add_u64 v[214:215], s[36:37], 0, v[136:137]
	s_add_i32 m0, s19, 0x2000
	s_nop 0
	global_load_lds_dwordx4 v[214:215], off
	v_lshl_add_u64 v[214:215], v[218:219], 0, s[6:7]
	s_mov_b32 m0, s49
	s_nop 0
	global_load_lds_dwordx4 v[214:215], off
	v_lshl_add_u64 v[214:215], v[220:221], 0, s[6:7]
	s_mov_b32 m0, s50
	s_nop 0
	global_load_lds_dwordx4 v[214:215], off
	s_waitcnt vmcnt(8)
	s_waitcnt lgkmcnt(0)
	s_barrier
	s_setprio 1
	s_waitcnt lgkmcnt(0)
	v_mfma_f32_16x16x32_bf16 v[62:65], v[144:147], v[182:185], v[62:65]
	v_mfma_f32_16x16x32_bf16 v[58:61], v[158:161], v[182:185], v[58:61]
	v_mfma_f32_16x16x32_bf16 v[54:57], v[144:147], v[190:193], v[54:57]
	v_mfma_f32_16x16x32_bf16 v[46:49], v[158:161], v[190:193], v[46:49]
	v_mfma_f32_16x16x32_bf16 v[38:41], v[144:147], v[198:201], v[38:41]
	v_mfma_f32_16x16x32_bf16 v[30:33], v[158:161], v[198:201], v[30:33]
	v_mfma_f32_16x16x32_bf16 v[22:25], v[144:147], v[206:209], v[22:25]
	v_mfma_f32_16x16x32_bf16 v[14:17], v[158:161], v[206:209], v[14:17]
	v_mfma_f32_16x16x32_bf16 v[62:65], v[154:157], v[186:189], v[62:65]
	v_mfma_f32_16x16x32_bf16 v[58:61], v[162:165], v[186:189], v[58:61]
	v_mfma_f32_16x16x32_bf16 v[54:57], v[154:157], v[194:197], v[54:57]
	v_mfma_f32_16x16x32_bf16 v[46:49], v[162:165], v[194:197], v[46:49]
	v_mfma_f32_16x16x32_bf16 v[38:41], v[154:157], v[202:205], v[38:41]
	v_mfma_f32_16x16x32_bf16 v[30:33], v[162:165], v[202:205], v[30:33]
	v_mfma_f32_16x16x32_bf16 v[22:25], v[154:157], v[210:213], v[22:25]
	v_mfma_f32_16x16x32_bf16 v[14:17], v[162:165], v[210:213], v[14:17]
	s_setprio 0
	s_setprio 1
	v_mfma_f32_16x16x32_bf16 v[50:53], v[166:169], v[182:185], v[50:53]
	v_mfma_f32_16x16x32_bf16 v[42:45], v[174:177], v[182:185], v[42:45]
	v_mfma_f32_16x16x32_bf16 v[34:37], v[166:169], v[190:193], v[34:37]
	v_mfma_f32_16x16x32_bf16 v[26:29], v[174:177], v[190:193], v[26:29]
	v_mfma_f32_16x16x32_bf16 v[18:21], v[166:169], v[198:201], v[18:21]
	v_mfma_f32_16x16x32_bf16 v[10:13], v[174:177], v[198:201], v[10:13]
	v_mfma_f32_16x16x32_bf16 v[6:9], v[166:169], v[206:209], v[6:9]
	v_mfma_f32_16x16x32_bf16 v[2:5], v[174:177], v[206:209], v[2:5]
	v_mfma_f32_16x16x32_bf16 v[50:53], v[170:173], v[186:189], v[50:53]
	v_mfma_f32_16x16x32_bf16 v[42:45], v[178:181], v[186:189], v[42:45]
	v_mfma_f32_16x16x32_bf16 v[34:37], v[170:173], v[194:197], v[34:37]
	v_mfma_f32_16x16x32_bf16 v[26:29], v[178:181], v[194:197], v[26:29]
	v_mfma_f32_16x16x32_bf16 v[18:21], v[170:173], v[202:205], v[18:21]
	v_mfma_f32_16x16x32_bf16 v[10:13], v[178:181], v[202:205], v[10:13]
	v_mfma_f32_16x16x32_bf16 v[6:9], v[170:173], v[210:213], v[6:9]
	v_mfma_f32_16x16x32_bf16 v[2:5], v[178:181], v[210:213], v[2:5]
	s_add_i32 s19, s17, 2
	s_add_u32 s34, s34, 0x100
	s_addc_u32 s35, s35, 0
	s_add_u32 s13, s13, 0x100
	s_addc_u32 s15, s15, 0
	s_cmp_ge_i32 s17, s78
	s_mov_b32 s17, s19
	s_setprio 0
	s_barrier
	s_cbranch_scc0 .LBB0_1522
	s_and_b64 vcc, exec, s[8:9]
	s_cbranch_vccz .LBB0_1525
	s_barrier

.LBB0_1699:
	ds_read_b128 v[146:149], v152
	ds_read_b128 v[156:159], v152 offset:1024
	ds_read_b128 v[160:163], v152 offset:2048
	ds_read_b128 v[164:167], v152 offset:3072
	ds_read_b128 v[168:171], v153
	ds_read_b128 v[172:175], v153 offset:1024
	ds_read_b128 v[176:179], v153 offset:2048
	ds_read_b128 v[180:183], v153 offset:3072
	s_add_u32 s22, s20, 0xfffc0080
	s_addc_u32 s23, s21, -1
	s_cmp_eq_u32 s52, 12
	s_cselect_b32 s31, s13, s23
	s_cselect_b32 s30, s48, s22
	s_cselect_b32 s23, s11, s51
	s_cselect_b32 s22, s49, s50
	v_lshl_add_u64 v[216:217], s[20:21], 0, v[138:139]
	s_add_i32 m0, s19, 0xc000
	ds_read_b128 v[184:187], v154
	ds_read_b128 v[188:191], v154 offset:1024
	ds_read_b128 v[192:195], v154 offset:2048
	ds_read_b128 v[196:199], v154 offset:3072
	ds_read_b128 v[200:203], v154 offset:4096
	ds_read_b128 v[204:207], v154 offset:5120
	ds_read_b128 v[208:211], v154 offset:6144
	ds_read_b128 v[212:215], v154 offset:7168
	global_load_lds_dwordx4 v[216:217], off
	v_lshl_add_u64 v[216:217], s[20:21], 0, v[140:141]
	s_add_i32 m0, s19, 0xe000
	s_nop 0
	global_load_lds_dwordx4 v[216:217], off
	s_waitcnt vmcnt(8)
	s_waitcnt lgkmcnt(0)
	s_barrier
	s_setprio 1
	s_waitcnt lgkmcnt(0)
	v_mfma_f32_16x16x32_bf16 v[126:129], v[146:149], v[184:187], v[126:129]
	v_mfma_f32_16x16x32_bf16 v[122:125], v[160:163], v[184:187], v[122:125]
	v_mfma_f32_16x16x32_bf16 v[110:113], v[146:149], v[192:195], v[110:113]
	v_mfma_f32_16x16x32_bf16 v[106:109], v[160:163], v[192:195], v[106:109]
	v_mfma_f32_16x16x32_bf16 v[94:97], v[146:149], v[200:203], v[94:97]
	v_mfma_f32_16x16x32_bf16 v[90:93], v[160:163], v[200:203], v[90:93]
	v_mfma_f32_16x16x32_bf16 v[78:81], v[146:149], v[208:211], v[78:81]
	v_mfma_f32_16x16x32_bf16 v[74:77], v[160:163], v[208:211], v[74:77]
	v_mfma_f32_16x16x32_bf16 v[126:129], v[156:159], v[188:191], v[126:129]
	v_mfma_f32_16x16x32_bf16 v[122:125], v[164:167], v[188:191], v[122:125]
	v_mfma_f32_16x16x32_bf16 v[110:113], v[156:159], v[196:199], v[110:113]
	v_mfma_f32_16x16x32_bf16 v[106:109], v[164:167], v[196:199], v[106:109]
	v_mfma_f32_16x16x32_bf16 v[94:97], v[156:159], v[204:207], v[94:97]
	v_mfma_f32_16x16x32_bf16 v[90:93], v[164:167], v[204:207], v[90:93]
	v_mfma_f32_16x16x32_bf16 v[78:81], v[156:159], v[212:215], v[78:81]
	v_mfma_f32_16x16x32_bf16 v[74:77], v[164:167], v[212:215], v[74:77]
	s_setprio 0
	s_setprio 1
	v_mfma_f32_16x16x32_bf16 v[118:121], v[168:171], v[184:187], v[118:121]
	v_mfma_f32_16x16x32_bf16 v[114:117], v[176:179], v[184:187], v[114:117]
	v_mfma_f32_16x16x32_bf16 v[102:105], v[168:171], v[192:195], v[102:105]
	v_mfma_f32_16x16x32_bf16 v[98:101], v[176:179], v[192:195], v[98:101]
	v_mfma_f32_16x16x32_bf16 v[86:89], v[168:171], v[200:203], v[86:89]
	v_mfma_f32_16x16x32_bf16 v[82:85], v[176:179], v[200:203], v[82:85]
	v_mfma_f32_16x16x32_bf16 v[70:73], v[168:171], v[208:211], v[70:73]
	v_mfma_f32_16x16x32_bf16 v[66:69], v[176:179], v[208:211], v[66:69]
	v_mfma_f32_16x16x32_bf16 v[118:121], v[172:175], v[188:191], v[118:121]
	v_mfma_f32_16x16x32_bf16 v[114:117], v[180:183], v[188:191], v[114:117]
	v_mfma_f32_16x16x32_bf16 v[102:105], v[172:175], v[196:199], v[102:105]
	v_mfma_f32_16x16x32_bf16 v[98:101], v[180:183], v[196:199], v[98:101]
	v_mfma_f32_16x16x32_bf16 v[86:89], v[172:175], v[204:207], v[86:89]
	v_mfma_f32_16x16x32_bf16 v[82:85], v[180:183], v[204:207], v[82:85]
	v_mfma_f32_16x16x32_bf16 v[70:73], v[172:175], v[212:215], v[70:73]
	v_mfma_f32_16x16x32_bf16 v[66:69], v[180:183], v[212:215], v[66:69]
	s_setprio 0
	s_barrier
	s_add_i32 s53, s44, s35
	v_lshl_add_u64 v[216:217], s[22:23], 0, v[132:133]
	s_mov_b32 m0, s53
	ds_read_b128 v[184:187], v154 offset:16384
	ds_read_b128 v[188:191], v154 offset:17408
	ds_read_b128 v[192:195], v154 offset:18432
	ds_read_b128 v[196:199], v154 offset:19456
	ds_read_b128 v[200:203], v154 offset:20480
	ds_read_b128 v[204:207], v154 offset:21504
	ds_read_b128 v[208:211], v154 offset:22528
	ds_read_b128 v[212:215], v154 offset:23552
	global_load_lds_dwordx4 v[216:217], off
	s_add_i32 m0, s53, 0x2000
	s_add_u32 s54, s22, 0x40000
	v_lshl_add_u64 v[218:219], s[22:23], 0, v[136:137]
	s_addc_u32 s55, s23, 0
	s_add_i32 s53, s45, s35
	global_load_lds_dwordx4 v[218:219], off
	v_lshl_add_u64 v[220:221], s[54:55], 0, v[132:133]
	s_mov_b32 m0, s53
	v_lshl_add_u64 v[222:223], s[30:31], 0, v[134:135]
	global_load_lds_dwordx4 v[220:221], off
	v_lshl_add_u64 v[220:221], s[54:55], 0, v[136:137]
	s_add_i32 m0, s53, 0x2000
	s_nop 0
	global_load_lds_dwordx4 v[220:221], off
	v_lshl_add_u64 v[220:221], s[30:31], 0, v[130:131]
	s_mov_b32 m0, s19
	s_nop 0
	global_load_lds_dwordx4 v[220:221], off
	s_mov_b32 m0, s37
	s_nop 0
	global_load_lds_dwordx4 v[222:223], off
	s_waitcnt vmcnt(8)
	s_waitcnt lgkmcnt(0)
	s_barrier
	s_setprio 1
	s_waitcnt lgkmcnt(0)
	v_mfma_f32_16x16x32_bf16 v[62:65], v[146:149], v[184:187], v[62:65]
	v_mfma_f32_16x16x32_bf16 v[58:61], v[160:163], v[184:187], v[58:61]
	v_mfma_f32_16x16x32_bf16 v[46:49], v[146:149], v[192:195], v[46:49]
	v_mfma_f32_16x16x32_bf16 v[42:45], v[160:163], v[192:195], v[42:45]
	v_mfma_f32_16x16x32_bf16 v[30:33], v[146:149], v[200:203], v[30:33]
	v_mfma_f32_16x16x32_bf16 v[26:29], v[160:163], v[200:203], v[26:29]
	v_mfma_f32_16x16x32_bf16 v[14:17], v[146:149], v[208:211], v[14:17]
	v_mfma_f32_16x16x32_bf16 v[10:13], v[160:163], v[208:211], v[10:13]
	v_mfma_f32_16x16x32_bf16 v[62:65], v[156:159], v[188:191], v[62:65]
	v_mfma_f32_16x16x32_bf16 v[58:61], v[164:167], v[188:191], v[58:61]
	v_mfma_f32_16x16x32_bf16 v[46:49], v[156:159], v[196:199], v[46:49]
	v_mfma_f32_16x16x32_bf16 v[42:45], v[164:167], v[196:199], v[42:45]
	v_mfma_f32_16x16x32_bf16 v[30:33], v[156:159], v[204:207], v[30:33]
	v_mfma_f32_16x16x32_bf16 v[26:29], v[164:167], v[204:207], v[26:29]
	v_mfma_f32_16x16x32_bf16 v[14:17], v[156:159], v[212:215], v[14:17]
	v_mfma_f32_16x16x32_bf16 v[10:13], v[164:167], v[212:215], v[10:13]
	s_setprio 0
	s_setprio 1
	v_mfma_f32_16x16x32_bf16 v[54:57], v[168:171], v[184:187], v[54:57]
	v_mfma_f32_16x16x32_bf16 v[50:53], v[176:179], v[184:187], v[50:53]
	v_mfma_f32_16x16x32_bf16 v[38:41], v[168:171], v[192:195], v[38:41]
	v_mfma_f32_16x16x32_bf16 v[34:37], v[176:179], v[192:195], v[34:37]
	v_mfma_f32_16x16x32_bf16 v[22:25], v[168:171], v[200:203], v[22:25]
	v_mfma_f32_16x16x32_bf16 v[18:21], v[176:179], v[200:203], v[18:21]
	v_mfma_f32_16x16x32_bf16 v[6:9], v[168:171], v[208:211], v[6:9]
	v_mfma_f32_16x16x32_bf16 v[2:5], v[176:179], v[208:211], v[2:5]
	v_mfma_f32_16x16x32_bf16 v[54:57], v[172:175], v[188:191], v[54:57]
	v_mfma_f32_16x16x32_bf16 v[50:53], v[180:183], v[188:191], v[50:53]
	v_mfma_f32_16x16x32_bf16 v[38:41], v[172:175], v[196:199], v[38:41]
	v_mfma_f32_16x16x32_bf16 v[34:37], v[180:183], v[196:199], v[34:37]
	v_mfma_f32_16x16x32_bf16 v[22:25], v[172:175], v[204:207], v[22:25]
	v_mfma_f32_16x16x32_bf16 v[18:21], v[180:183], v[204:207], v[18:21]
	v_mfma_f32_16x16x32_bf16 v[6:9], v[172:175], v[212:215], v[6:9]
	v_mfma_f32_16x16x32_bf16 v[2:5], v[180:183], v[212:215], v[2:5]
	s_setprio 0
	s_barrier
	s_add_i32 s53, 0, 0x18000
	v_add_u32_e32 v155, s53, v150
	s_add_i32 s54, 0, 0x1c000
	ds_read_b128 v[146:149], v155
	ds_read_b128 v[156:159], v155 offset:1024
	ds_read_b128 v[160:163], v155 offset:2048
	ds_read_b128 v[164:167], v155 offset:3072
	v_add_u32_e32 v155, s54, v150
	ds_read_b128 v[168:171], v155
	ds_read_b128 v[172:175], v155 offset:1024
	ds_read_b128 v[176:179], v155 offset:2048
	ds_read_b128 v[180:183], v155 offset:3072
	s_add_u32 s30, s30, 0x40000
	s_addc_u32 s31, s31, 0
	s_mov_b32 m0, s38
	v_lshl_add_u64 v[224:225], s[30:31], 0, v[130:131]
	ds_read_b128 v[184:187], v154 offset:32768
	ds_read_b128 v[188:191], v154 offset:33792
	ds_read_b128 v[192:195], v154 offset:34816
	ds_read_b128 v[196:199], v154 offset:35840
	ds_read_b128 v[200:203], v154 offset:36864
	ds_read_b128 v[204:207], v154 offset:37888
	ds_read_b128 v[208:211], v154 offset:38912
	ds_read_b128 v[212:215], v154 offset:39936
	global_load_lds_dwordx4 v[224:225], off
	v_lshl_add_u64 v[224:225], s[30:31], 0, v[134:135]
	s_mov_b32 m0, s39
	s_nop 0
	global_load_lds_dwordx4 v[224:225], off
	s_waitcnt vmcnt(8)
	s_waitcnt lgkmcnt(0)
	s_barrier
	s_setprio 1
	s_waitcnt lgkmcnt(0)
	v_mfma_f32_16x16x32_bf16 v[126:129], v[146:149], v[184:187], v[126:129]
	v_mfma_f32_16x16x32_bf16 v[122:125], v[160:163], v[184:187], v[122:125]
	v_mfma_f32_16x16x32_bf16 v[110:113], v[146:149], v[192:195], v[110:113]
	v_mfma_f32_16x16x32_bf16 v[106:109], v[160:163], v[192:195], v[106:109]
	v_mfma_f32_16x16x32_bf16 v[94:97], v[146:149], v[200:203], v[94:97]
	v_mfma_f32_16x16x32_bf16 v[90:93], v[160:163], v[200:203], v[90:93]
	v_mfma_f32_16x16x32_bf16 v[78:81], v[146:149], v[208:211], v[78:81]
	v_mfma_f32_16x16x32_bf16 v[74:77], v[160:163], v[208:211], v[74:77]
	v_mfma_f32_16x16x32_bf16 v[126:129], v[156:159], v[188:191], v[126:129]
	v_mfma_f32_16x16x32_bf16 v[122:125], v[164:167], v[188:191], v[122:125]
	v_mfma_f32_16x16x32_bf16 v[110:113], v[156:159], v[196:199], v[110:113]
	v_mfma_f32_16x16x32_bf16 v[106:109], v[164:167], v[196:199], v[106:109]
	v_mfma_f32_16x16x32_bf16 v[94:97], v[156:159], v[204:207], v[94:97]
	v_mfma_f32_16x16x32_bf16 v[90:93], v[164:167], v[204:207], v[90:93]
	v_mfma_f32_16x16x32_bf16 v[78:81], v[156:159], v[212:215], v[78:81]
	v_mfma_f32_16x16x32_bf16 v[74:77], v[164:167], v[212:215], v[74:77]
	s_setprio 0
	s_setprio 1
	v_mfma_f32_16x16x32_bf16 v[118:121], v[168:171], v[184:187], v[118:121]
	v_mfma_f32_16x16x32_bf16 v[114:117], v[176:179], v[184:187], v[114:117]
	v_mfma_f32_16x16x32_bf16 v[102:105], v[168:171], v[192:195], v[102:105]
	v_mfma_f32_16x16x32_bf16 v[98:101], v[176:179], v[192:195], v[98:101]
	v_mfma_f32_16x16x32_bf16 v[86:89], v[168:171], v[200:203], v[86:89]
	v_mfma_f32_16x16x32_bf16 v[82:85], v[176:179], v[200:203], v[82:85]
	v_mfma_f32_16x16x32_bf16 v[70:73], v[168:171], v[208:211], v[70:73]
	v_mfma_f32_16x16x32_bf16 v[66:69], v[176:179], v[208:211], v[66:69]
	v_mfma_f32_16x16x32_bf16 v[118:121], v[172:175], v[188:191], v[118:121]
	v_mfma_f32_16x16x32_bf16 v[114:117], v[180:183], v[188:191], v[114:117]
	v_mfma_f32_16x16x32_bf16 v[102:105], v[172:175], v[196:199], v[102:105]
	v_mfma_f32_16x16x32_bf16 v[98:101], v[180:183], v[196:199], v[98:101]
	v_mfma_f32_16x16x32_bf16 v[86:89], v[172:175], v[204:207], v[86:89]
	v_mfma_f32_16x16x32_bf16 v[82:85], v[180:183], v[204:207], v[82:85]
	v_mfma_f32_16x16x32_bf16 v[70:73], v[172:175], v[212:215], v[70:73]
	v_mfma_f32_16x16x32_bf16 v[66:69], v[180:183], v[212:215], v[66:69]
	s_setprio 0
	s_barrier
	s_add_i32 s30, s53, s35
	v_lshl_add_u64 v[216:217], v[216:217], 0, s[6:7]
	s_mov_b32 m0, s30
	ds_read_b128 v[184:187], v154 offset:49152
	ds_read_b128 v[188:191], v154 offset:50176
	ds_read_b128 v[192:195], v154 offset:51200
	ds_read_b128 v[196:199], v154 offset:52224
	ds_read_b128 v[200:203], v154 offset:53248
	ds_read_b128 v[204:207], v154 offset:54272
	ds_read_b128 v[208:211], v154 offset:55296
	ds_read_b128 v[212:215], v154 offset:56320
	global_load_lds_dwordx4 v[216:217], off
	s_add_i32 m0, s30, 0x2000
	s_add_u32 s22, s22, 0x40080
	v_lshl_add_u64 v[216:217], v[218:219], 0, s[6:7]
	s_addc_u32 s23, s23, 0
	s_add_i32 s30, s54, s35
	global_load_lds_dwordx4 v[216:217], off
	v_lshl_add_u64 v[216:217], s[22:23], 0, v[132:133]
	s_mov_b32 m0, s30
	s_nop 0
	global_load_lds_dwordx4 v[216:217], off
	v_lshl_add_u64 v[216:217], s[22:23], 0, v[136:137]
	s_add_i32 m0, s30, 0x2000
	s_nop 0
	global_load_lds_dwordx4 v[216:217], off
	v_lshl_add_u64 v[216:217], v[220:221], 0, s[6:7]
	s_mov_b32 m0, s42
	s_nop 0
	global_load_lds_dwordx4 v[216:217], off
	v_lshl_add_u64 v[216:217], v[222:223], 0, s[6:7]
	s_mov_b32 m0, s43
	s_nop 0
	global_load_lds_dwordx4 v[216:217], off
	s_waitcnt vmcnt(8)
	s_waitcnt lgkmcnt(0)
	s_barrier
	s_setprio 1
	s_waitcnt lgkmcnt(0)
	v_mfma_f32_16x16x32_bf16 v[62:65], v[146:149], v[184:187], v[62:65]
	v_mfma_f32_16x16x32_bf16 v[58:61], v[160:163], v[184:187], v[58:61]
	v_mfma_f32_16x16x32_bf16 v[46:49], v[146:149], v[192:195], v[46:49]
	v_mfma_f32_16x16x32_bf16 v[42:45], v[160:163], v[192:195], v[42:45]
	v_mfma_f32_16x16x32_bf16 v[30:33], v[146:149], v[200:203], v[30:33]
	v_mfma_f32_16x16x32_bf16 v[26:29], v[160:163], v[200:203], v[26:29]
	v_mfma_f32_16x16x32_bf16 v[14:17], v[146:149], v[208:211], v[14:17]
	v_mfma_f32_16x16x32_bf16 v[10:13], v[160:163], v[208:211], v[10:13]
	v_mfma_f32_16x16x32_bf16 v[62:65], v[156:159], v[188:191], v[62:65]
	v_mfma_f32_16x16x32_bf16 v[58:61], v[164:167], v[188:191], v[58:61]
	v_mfma_f32_16x16x32_bf16 v[46:49], v[156:159], v[196:199], v[46:49]
	v_mfma_f32_16x16x32_bf16 v[42:45], v[164:167], v[196:199], v[42:45]
	v_mfma_f32_16x16x32_bf16 v[30:33], v[156:159], v[204:207], v[30:33]
	v_mfma_f32_16x16x32_bf16 v[26:29], v[164:167], v[204:207], v[26:29]
	v_mfma_f32_16x16x32_bf16 v[14:17], v[156:159], v[212:215], v[14:17]
	v_mfma_f32_16x16x32_bf16 v[10:13], v[164:167], v[212:215], v[10:13]
	s_setprio 0
	s_setprio 1
	v_mfma_f32_16x16x32_bf16 v[54:57], v[168:171], v[184:187], v[54:57]
	v_mfma_f32_16x16x32_bf16 v[50:53], v[176:179], v[184:187], v[50:53]
	v_mfma_f32_16x16x32_bf16 v[38:41], v[168:171], v[192:195], v[38:41]
	v_mfma_f32_16x16x32_bf16 v[34:37], v[176:179], v[192:195], v[34:37]
	v_mfma_f32_16x16x32_bf16 v[22:25], v[168:171], v[200:203], v[22:25]
	v_mfma_f32_16x16x32_bf16 v[18:21], v[176:179], v[200:203], v[18:21]
	v_mfma_f32_16x16x32_bf16 v[6:9], v[168:171], v[208:211], v[6:9]
	v_mfma_f32_16x16x32_bf16 v[2:5], v[176:179], v[208:211], v[2:5]
	v_mfma_f32_16x16x32_bf16 v[54:57], v[172:175], v[188:191], v[54:57]
	v_mfma_f32_16x16x32_bf16 v[50:53], v[180:183], v[188:191], v[50:53]
	v_mfma_f32_16x16x32_bf16 v[38:41], v[172:175], v[196:199], v[38:41]
	v_mfma_f32_16x16x32_bf16 v[34:37], v[180:183], v[196:199], v[34:37]
	v_mfma_f32_16x16x32_bf16 v[22:25], v[172:175], v[204:207], v[22:25]
	v_mfma_f32_16x16x32_bf16 v[18:21], v[180:183], v[204:207], v[18:21]
	v_mfma_f32_16x16x32_bf16 v[6:9], v[172:175], v[212:215], v[6:9]
	v_mfma_f32_16x16x32_bf16 v[2:5], v[180:183], v[212:215], v[2:5]
	s_add_i32 s52, s52, 2
	s_add_u32 s20, s20, 0x100
	s_addc_u32 s21, s21, 0
	s_add_u32 s50, s50, 0x100
	s_addc_u32 s51, s51, 0
	s_cmp_gt_u32 s52, 13
	s_setprio 0
	s_barrier
	s_cbranch_scc0 .LBB0_1699
	s_and_b64 vcc, exec, s[8:9]
	s_cbranch_vccz .LBB0_1702
	s_barrier

.LBB0_1788:
	ds_read_b128 v[142:145], v149
	ds_read_b128 v[152:155], v149 offset:1024
	ds_read_b128 v[156:159], v149 offset:2048
	ds_read_b128 v[160:163], v149 offset:3072
	ds_read_b128 v[164:167], v150
	ds_read_b128 v[168:171], v150 offset:1024
	ds_read_b128 v[172:175], v150 offset:2048
	ds_read_b128 v[176:179], v150 offset:3072
	s_add_u32 s20, s18, 0xfff50080
	s_addc_u32 s21, s19, -1
	s_cmp_eq_u32 s75, s77
	s_cselect_b32 s23, s15, s21
	s_cselect_b32 s22, s14, s20
	s_cselect_b32 s21, s17, s76
	s_cselect_b32 s20, s16, s13
	v_lshl_add_u64 v[212:213], s[18:19], 0, v[136:137]
	s_add_i32 m0, s34, 0xc000
	ds_read_b128 v[180:183], v151
	ds_read_b128 v[184:187], v151 offset:1024
	ds_read_b128 v[188:191], v151 offset:2048
	ds_read_b128 v[192:195], v151 offset:3072
	ds_read_b128 v[196:199], v151 offset:4096
	ds_read_b128 v[200:203], v151 offset:5120
	ds_read_b128 v[204:207], v151 offset:6144
	ds_read_b128 v[208:211], v151 offset:7168
	global_load_lds_dwordx4 v[212:213], off
	v_lshl_add_u64 v[212:213], s[18:19], 0, v[138:139]
	s_add_i32 m0, s34, 0xe000
	s_nop 0
	global_load_lds_dwordx4 v[212:213], off
	s_waitcnt vmcnt(8)
	s_waitcnt lgkmcnt(0)
	s_barrier
	s_setprio 1
	s_waitcnt lgkmcnt(0)
	v_mfma_f32_16x16x32_bf16 v[124:127], v[142:145], v[180:183], v[124:127]
	v_mfma_f32_16x16x32_bf16 v[120:123], v[156:159], v[180:183], v[120:123]
	v_mfma_f32_16x16x32_bf16 v[116:119], v[142:145], v[188:191], v[116:119]
	v_mfma_f32_16x16x32_bf16 v[108:111], v[156:159], v[188:191], v[108:111]
	v_mfma_f32_16x16x32_bf16 v[100:103], v[142:145], v[196:199], v[100:103]
	v_mfma_f32_16x16x32_bf16 v[92:95], v[156:159], v[196:199], v[92:95]
	v_mfma_f32_16x16x32_bf16 v[84:87], v[142:145], v[204:207], v[84:87]
	v_mfma_f32_16x16x32_bf16 v[76:79], v[156:159], v[204:207], v[76:79]
	v_mfma_f32_16x16x32_bf16 v[124:127], v[152:155], v[184:187], v[124:127]
	v_mfma_f32_16x16x32_bf16 v[120:123], v[160:163], v[184:187], v[120:123]
	v_mfma_f32_16x16x32_bf16 v[116:119], v[152:155], v[192:195], v[116:119]
	v_mfma_f32_16x16x32_bf16 v[108:111], v[160:163], v[192:195], v[108:111]
	v_mfma_f32_16x16x32_bf16 v[100:103], v[152:155], v[200:203], v[100:103]
	v_mfma_f32_16x16x32_bf16 v[92:95], v[160:163], v[200:203], v[92:95]
	v_mfma_f32_16x16x32_bf16 v[84:87], v[152:155], v[208:211], v[84:87]
	v_mfma_f32_16x16x32_bf16 v[76:79], v[160:163], v[208:211], v[76:79]
	s_setprio 0
	s_setprio 1
	v_mfma_f32_16x16x32_bf16 v[112:115], v[164:167], v[180:183], v[112:115]
	v_mfma_f32_16x16x32_bf16 v[104:107], v[172:175], v[180:183], v[104:107]
	v_mfma_f32_16x16x32_bf16 v[96:99], v[164:167], v[188:191], v[96:99]
	v_mfma_f32_16x16x32_bf16 v[88:91], v[172:175], v[188:191], v[88:91]
	v_mfma_f32_16x16x32_bf16 v[80:83], v[164:167], v[196:199], v[80:83]
	v_mfma_f32_16x16x32_bf16 v[72:75], v[172:175], v[196:199], v[72:75]
	v_mfma_f32_16x16x32_bf16 v[68:71], v[164:167], v[204:207], v[68:71]
	v_mfma_f32_16x16x32_bf16 v[64:67], v[172:175], v[204:207], v[64:67]
	v_mfma_f32_16x16x32_bf16 v[112:115], v[168:171], v[184:187], v[112:115]
	v_mfma_f32_16x16x32_bf16 v[104:107], v[176:179], v[184:187], v[104:107]
	v_mfma_f32_16x16x32_bf16 v[96:99], v[168:171], v[192:195], v[96:99]
	v_mfma_f32_16x16x32_bf16 v[88:91], v[176:179], v[192:195], v[88:91]
	v_mfma_f32_16x16x32_bf16 v[80:83], v[168:171], v[200:203], v[80:83]
	v_mfma_f32_16x16x32_bf16 v[72:75], v[176:179], v[200:203], v[72:75]
	v_mfma_f32_16x16x32_bf16 v[68:71], v[168:171], v[208:211], v[68:71]
	v_mfma_f32_16x16x32_bf16 v[64:67], v[176:179], v[208:211], v[64:67]
	s_setprio 0
	s_barrier
	s_add_i32 s78, s48, s31
	v_lshl_add_u64 v[212:213], s[20:21], 0, v[130:131]
	s_mov_b32 m0, s78
	ds_read_b128 v[180:183], v151 offset:16384
	ds_read_b128 v[184:187], v151 offset:17408
	ds_read_b128 v[188:191], v151 offset:18432
	ds_read_b128 v[192:195], v151 offset:19456
	ds_read_b128 v[196:199], v151 offset:20480
	ds_read_b128 v[200:203], v151 offset:21504
	ds_read_b128 v[204:207], v151 offset:22528
	ds_read_b128 v[208:211], v151 offset:23552
	global_load_lds_dwordx4 v[212:213], off
	s_add_i32 m0, s78, 0x2000
	s_add_u32 s78, s20, 0xb0000
	v_lshl_add_u64 v[214:215], s[20:21], 0, v[134:135]
	s_addc_u32 s79, s21, 0
	s_add_i32 s80, s49, s31
	global_load_lds_dwordx4 v[214:215], off
	v_lshl_add_u64 v[216:217], s[78:79], 0, v[130:131]
	s_mov_b32 m0, s80
	v_lshl_add_u64 v[218:219], s[22:23], 0, v[132:133]
	global_load_lds_dwordx4 v[216:217], off
	v_lshl_add_u64 v[216:217], s[78:79], 0, v[134:135]
	s_add_i32 m0, s80, 0x2000
	s_nop 0
	global_load_lds_dwordx4 v[216:217], off
	v_lshl_add_u64 v[216:217], s[22:23], 0, v[128:129]
	s_mov_b32 m0, s34
	s_nop 0
	global_load_lds_dwordx4 v[216:217], off
	s_mov_b32 m0, s35
	s_nop 0
	global_load_lds_dwordx4 v[218:219], off
	s_waitcnt vmcnt(8)
	s_waitcnt lgkmcnt(0)
	s_barrier
	s_setprio 1
	s_waitcnt lgkmcnt(0)
	v_mfma_f32_16x16x32_bf16 v[60:63], v[142:145], v[180:183], v[60:63]
	v_mfma_f32_16x16x32_bf16 v[56:59], v[156:159], v[180:183], v[56:59]
	v_mfma_f32_16x16x32_bf16 v[52:55], v[142:145], v[188:191], v[52:55]
	v_mfma_f32_16x16x32_bf16 v[44:47], v[156:159], v[188:191], v[44:47]
	v_mfma_f32_16x16x32_bf16 v[36:39], v[142:145], v[196:199], v[36:39]
	v_mfma_f32_16x16x32_bf16 v[28:31], v[156:159], v[196:199], v[28:31]
	v_mfma_f32_16x16x32_bf16 v[20:23], v[142:145], v[204:207], v[20:23]
	v_mfma_f32_16x16x32_bf16 v[12:15], v[156:159], v[204:207], v[12:15]
	v_mfma_f32_16x16x32_bf16 v[60:63], v[152:155], v[184:187], v[60:63]
	v_mfma_f32_16x16x32_bf16 v[56:59], v[160:163], v[184:187], v[56:59]
	v_mfma_f32_16x16x32_bf16 v[52:55], v[152:155], v[192:195], v[52:55]
	v_mfma_f32_16x16x32_bf16 v[44:47], v[160:163], v[192:195], v[44:47]
	v_mfma_f32_16x16x32_bf16 v[36:39], v[152:155], v[200:203], v[36:39]
	v_mfma_f32_16x16x32_bf16 v[28:31], v[160:163], v[200:203], v[28:31]
	v_mfma_f32_16x16x32_bf16 v[20:23], v[152:155], v[208:211], v[20:23]
	v_mfma_f32_16x16x32_bf16 v[12:15], v[160:163], v[208:211], v[12:15]
	s_setprio 0
	s_setprio 1
	v_mfma_f32_16x16x32_bf16 v[48:51], v[164:167], v[180:183], v[48:51]
	v_mfma_f32_16x16x32_bf16 v[40:43], v[172:175], v[180:183], v[40:43]
	v_mfma_f32_16x16x32_bf16 v[32:35], v[164:167], v[188:191], v[32:35]
	v_mfma_f32_16x16x32_bf16 v[24:27], v[172:175], v[188:191], v[24:27]
	v_mfma_f32_16x16x32_bf16 v[16:19], v[164:167], v[196:199], v[16:19]
	v_mfma_f32_16x16x32_bf16 v[8:11], v[172:175], v[196:199], v[8:11]
	v_mfma_f32_16x16x32_bf16 v[4:7], v[164:167], v[204:207], v[4:7]
	v_mfma_f32_16x16x32_bf16 v[0:3], v[172:175], v[204:207], v[0:3]
	v_mfma_f32_16x16x32_bf16 v[48:51], v[168:171], v[184:187], v[48:51]
	v_mfma_f32_16x16x32_bf16 v[40:43], v[176:179], v[184:187], v[40:43]
	v_mfma_f32_16x16x32_bf16 v[32:35], v[168:171], v[192:195], v[32:35]
	v_mfma_f32_16x16x32_bf16 v[24:27], v[176:179], v[192:195], v[24:27]
	v_mfma_f32_16x16x32_bf16 v[16:19], v[168:171], v[200:203], v[16:19]
	v_mfma_f32_16x16x32_bf16 v[8:11], v[176:179], v[200:203], v[8:11]
	v_mfma_f32_16x16x32_bf16 v[4:7], v[168:171], v[208:211], v[4:7]
	v_mfma_f32_16x16x32_bf16 v[0:3], v[176:179], v[208:211], v[0:3]
	s_setprio 0
	s_barrier
	s_add_i32 s78, 0, 0x18000
	s_add_i32 s79, 0, 0x1c000
	v_add_u32_e32 v160, s78, v147
	v_add_u32_e32 v176, s79, v147
	ds_read_b128 v[142:145], v160
	ds_read_b128 v[152:155], v160 offset:1024
	ds_read_b128 v[156:159], v160 offset:2048
	ds_read_b128 v[160:163], v160 offset:3072
	ds_read_b128 v[164:167], v176
	ds_read_b128 v[168:171], v176 offset:1024
	ds_read_b128 v[172:175], v176 offset:2048
	ds_read_b128 v[176:179], v176 offset:3072
	s_add_u32 s22, s22, 0xb0000
	s_addc_u32 s23, s23, 0
	s_mov_b32 m0, s36
	v_lshl_add_u64 v[220:221], s[22:23], 0, v[128:129]
	ds_read_b128 v[180:183], v151 offset:32768
	ds_read_b128 v[184:187], v151 offset:33792
	ds_read_b128 v[188:191], v151 offset:34816
	ds_read_b128 v[192:195], v151 offset:35840
	ds_read_b128 v[196:199], v151 offset:36864
	ds_read_b128 v[200:203], v151 offset:37888
	ds_read_b128 v[204:207], v151 offset:38912
	ds_read_b128 v[208:211], v151 offset:39936
	global_load_lds_dwordx4 v[220:221], off
	v_lshl_add_u64 v[220:221], s[22:23], 0, v[132:133]
	s_mov_b32 m0, s37
	s_nop 0
	global_load_lds_dwordx4 v[220:221], off
	s_waitcnt vmcnt(8)
	s_waitcnt lgkmcnt(0)
	s_barrier
	s_setprio 1
	s_waitcnt lgkmcnt(0)
	v_mfma_f32_16x16x32_bf16 v[124:127], v[142:145], v[180:183], v[124:127]
	v_mfma_f32_16x16x32_bf16 v[120:123], v[156:159], v[180:183], v[120:123]
	v_mfma_f32_16x16x32_bf16 v[116:119], v[142:145], v[188:191], v[116:119]
	v_mfma_f32_16x16x32_bf16 v[108:111], v[156:159], v[188:191], v[108:111]
	v_mfma_f32_16x16x32_bf16 v[100:103], v[142:145], v[196:199], v[100:103]
	v_mfma_f32_16x16x32_bf16 v[92:95], v[156:159], v[196:199], v[92:95]
	v_mfma_f32_16x16x32_bf16 v[84:87], v[142:145], v[204:207], v[84:87]
	v_mfma_f32_16x16x32_bf16 v[76:79], v[156:159], v[204:207], v[76:79]
	v_mfma_f32_16x16x32_bf16 v[124:127], v[152:155], v[184:187], v[124:127]
	v_mfma_f32_16x16x32_bf16 v[120:123], v[160:163], v[184:187], v[120:123]
	v_mfma_f32_16x16x32_bf16 v[116:119], v[152:155], v[192:195], v[116:119]
	v_mfma_f32_16x16x32_bf16 v[108:111], v[160:163], v[192:195], v[108:111]
	v_mfma_f32_16x16x32_bf16 v[100:103], v[152:155], v[200:203], v[100:103]
	v_mfma_f32_16x16x32_bf16 v[92:95], v[160:163], v[200:203], v[92:95]
	v_mfma_f32_16x16x32_bf16 v[84:87], v[152:155], v[208:211], v[84:87]
	v_mfma_f32_16x16x32_bf16 v[76:79], v[160:163], v[208:211], v[76:79]
	s_setprio 0
	s_setprio 1
	v_mfma_f32_16x16x32_bf16 v[112:115], v[164:167], v[180:183], v[112:115]
	v_mfma_f32_16x16x32_bf16 v[104:107], v[172:175], v[180:183], v[104:107]
	v_mfma_f32_16x16x32_bf16 v[96:99], v[164:167], v[188:191], v[96:99]
	v_mfma_f32_16x16x32_bf16 v[88:91], v[172:175], v[188:191], v[88:91]
	v_mfma_f32_16x16x32_bf16 v[80:83], v[164:167], v[196:199], v[80:83]
	v_mfma_f32_16x16x32_bf16 v[72:75], v[172:175], v[196:199], v[72:75]
	v_mfma_f32_16x16x32_bf16 v[68:71], v[164:167], v[204:207], v[68:71]
	v_mfma_f32_16x16x32_bf16 v[64:67], v[172:175], v[204:207], v[64:67]
	v_mfma_f32_16x16x32_bf16 v[112:115], v[168:171], v[184:187], v[112:115]
	v_mfma_f32_16x16x32_bf16 v[104:107], v[176:179], v[184:187], v[104:107]
	v_mfma_f32_16x16x32_bf16 v[96:99], v[168:171], v[192:195], v[96:99]
	v_mfma_f32_16x16x32_bf16 v[88:91], v[176:179], v[192:195], v[88:91]
	v_mfma_f32_16x16x32_bf16 v[80:83], v[168:171], v[200:203], v[80:83]
	v_mfma_f32_16x16x32_bf16 v[72:75], v[176:179], v[200:203], v[72:75]
	v_mfma_f32_16x16x32_bf16 v[68:71], v[168:171], v[208:211], v[68:71]
	v_mfma_f32_16x16x32_bf16 v[64:67], v[176:179], v[208:211], v[64:67]
	s_setprio 0
	s_barrier
	s_add_i32 s22, s78, s31
	v_lshl_add_u64 v[212:213], v[212:213], 0, s[6:7]
	s_mov_b32 m0, s22
	ds_read_b128 v[180:183], v151 offset:49152
	ds_read_b128 v[184:187], v151 offset:50176
	ds_read_b128 v[188:191], v151 offset:51200
	ds_read_b128 v[192:195], v151 offset:52224
	ds_read_b128 v[196:199], v151 offset:53248
	ds_read_b128 v[200:203], v151 offset:54272
	ds_read_b128 v[204:207], v151 offset:55296
	ds_read_b128 v[208:211], v151 offset:56320
	global_load_lds_dwordx4 v[212:213], off
	s_add_i32 m0, s22, 0x2000
	s_add_u32 s20, s20, 0xb0080
	v_lshl_add_u64 v[212:213], v[214:215], 0, s[6:7]
	s_addc_u32 s21, s21, 0
	s_add_i32 s22, s79, s31
	global_load_lds_dwordx4 v[212:213], off
	v_lshl_add_u64 v[212:213], s[20:21], 0, v[130:131]
	s_mov_b32 m0, s22
	s_nop 0
	global_load_lds_dwordx4 v[212:213], off
	v_lshl_add_u64 v[212:213], s[20:21], 0, v[134:135]
	s_add_i32 m0, s22, 0x2000
	s_nop 0
	global_load_lds_dwordx4 v[212:213], off
	v_lshl_add_u64 v[212:213], v[216:217], 0, s[6:7]
	s_mov_b32 m0, s42
	s_nop 0
	global_load_lds_dwordx4 v[212:213], off
	v_lshl_add_u64 v[212:213], v[218:219], 0, s[6:7]
	s_mov_b32 m0, s43
	s_nop 0
	global_load_lds_dwordx4 v[212:213], off
	s_waitcnt vmcnt(8)
	s_waitcnt lgkmcnt(0)
	s_barrier
	s_setprio 1
	s_waitcnt lgkmcnt(0)
	v_mfma_f32_16x16x32_bf16 v[60:63], v[142:145], v[180:183], v[60:63]
	v_mfma_f32_16x16x32_bf16 v[56:59], v[156:159], v[180:183], v[56:59]
	v_mfma_f32_16x16x32_bf16 v[52:55], v[142:145], v[188:191], v[52:55]
	v_mfma_f32_16x16x32_bf16 v[44:47], v[156:159], v[188:191], v[44:47]
	v_mfma_f32_16x16x32_bf16 v[36:39], v[142:145], v[196:199], v[36:39]
	v_mfma_f32_16x16x32_bf16 v[28:31], v[156:159], v[196:199], v[28:31]
	v_mfma_f32_16x16x32_bf16 v[20:23], v[142:145], v[204:207], v[20:23]
	v_mfma_f32_16x16x32_bf16 v[12:15], v[156:159], v[204:207], v[12:15]
	v_mfma_f32_16x16x32_bf16 v[60:63], v[152:155], v[184:187], v[60:63]
	v_mfma_f32_16x16x32_bf16 v[56:59], v[160:163], v[184:187], v[56:59]
	v_mfma_f32_16x16x32_bf16 v[52:55], v[152:155], v[192:195], v[52:55]
	v_mfma_f32_16x16x32_bf16 v[44:47], v[160:163], v[192:195], v[44:47]
	v_mfma_f32_16x16x32_bf16 v[36:39], v[152:155], v[200:203], v[36:39]
	v_mfma_f32_16x16x32_bf16 v[28:31], v[160:163], v[200:203], v[28:31]
	v_mfma_f32_16x16x32_bf16 v[20:23], v[152:155], v[208:211], v[20:23]
	v_mfma_f32_16x16x32_bf16 v[12:15], v[160:163], v[208:211], v[12:15]
	s_setprio 0
	s_setprio 1
	v_mfma_f32_16x16x32_bf16 v[48:51], v[164:167], v[180:183], v[48:51]
	v_mfma_f32_16x16x32_bf16 v[40:43], v[172:175], v[180:183], v[40:43]
	v_mfma_f32_16x16x32_bf16 v[32:35], v[164:167], v[188:191], v[32:35]
	v_mfma_f32_16x16x32_bf16 v[24:27], v[172:175], v[188:191], v[24:27]
	v_mfma_f32_16x16x32_bf16 v[16:19], v[164:167], v[196:199], v[16:19]
	v_mfma_f32_16x16x32_bf16 v[8:11], v[172:175], v[196:199], v[8:11]
	v_mfma_f32_16x16x32_bf16 v[4:7], v[164:167], v[204:207], v[4:7]
	v_mfma_f32_16x16x32_bf16 v[0:3], v[172:175], v[204:207], v[0:3]
	v_mfma_f32_16x16x32_bf16 v[48:51], v[168:171], v[184:187], v[48:51]
	v_mfma_f32_16x16x32_bf16 v[40:43], v[176:179], v[184:187], v[40:43]
	v_mfma_f32_16x16x32_bf16 v[32:35], v[168:171], v[192:195], v[32:35]
	v_mfma_f32_16x16x32_bf16 v[24:27], v[176:179], v[192:195], v[24:27]
	v_mfma_f32_16x16x32_bf16 v[16:19], v[168:171], v[200:203], v[16:19]
	v_mfma_f32_16x16x32_bf16 v[8:11], v[176:179], v[200:203], v[8:11]
	v_mfma_f32_16x16x32_bf16 v[4:7], v[168:171], v[208:211], v[4:7]
	v_mfma_f32_16x16x32_bf16 v[0:3], v[176:179], v[208:211], v[0:3]
	s_add_i32 s20, s77, 2
	s_add_u32 s18, s18, 0x100
	s_addc_u32 s19, s19, 0
	s_add_u32 s13, s13, 0x100
	s_addc_u32 s76, s76, 0
	s_cmp_ge_i32 s77, s75
	s_mov_b32 s77, s20
	s_setprio 0
	s_barrier
	s_cbranch_scc0 .LBB0_1788
	s_and_b64 vcc, exec, s[8:9]
	s_cbranch_vccz .LBB0_1791
	s_barrier
